# S5 scan recurrence with scalar mul / fma instead of packed f32 ops (packed f32 VALU shares the matrix pipe with the other wave's f32 MFMAs)
# speedup vs baseline: 1.0087x; 1.0027x over previous
; __device__ __forceinline__ void s5_pass1(const Params& p, int layer, int task, char* sm) {
;     ...
;   for (int l = 0; l < 128; l++) S5_STEP(sU + l * 16)
.LBB0_477:
	v_mov_b32_e32 v37, v38
	s_nop 1
	v_permlane32_swap_b32_e32 v16, v12
	v_permlane32_swap_b32_e32 v17, v13
	v_permlane32_swap_b32_e32 v18, v14
	v_permlane32_swap_b32_e32 v19, v15
	v_permlane32_swap_b32_e32 v20, v8
	v_permlane32_swap_b32_e32 v21, v9
	v_permlane32_swap_b32_e32 v22, v10
	v_permlane32_swap_b32_e32 v23, v11
	v_permlane32_swap_b32_e32 v24, v4
	v_permlane32_swap_b32_e32 v25, v5
	v_permlane32_swap_b32_e32 v26, v6
	v_permlane32_swap_b32_e32 v27, v7
	v_permlane32_swap_b32_e32 v28, v0
	v_permlane32_swap_b32_e32 v29, v1
	v_permlane32_swap_b32_e32 v30, v2
	v_permlane32_swap_b32_e32 v31, v3
	v_and_b32_e32 v186, 31, v202
	v_lshrrev_b32_e32 v187, 5, v202
	v_lshlrev_b32_e32 v186, 6, v186
	v_lshl_add_u32 v186, v187, 2, v186
	v_add_u32_e32 v186, v41, v186
	ds_read2_b32 v[178:179], v186 offset0:0 offset1:2
	ds_read2_b32 v[180:181], v186 offset0:4 offset1:6
	ds_read2_b32 v[182:183], v186 offset0:8 offset1:10
	ds_read2_b32 v[184:185], v186 offset0:12 offset1:14
	s_waitcnt lgkmcnt(0)
	v_add_u32_e32 v186, 0x800, v186
	v_mfma_f32_32x32x2_f32 v[108:123], v178, v16, 0
	v_mfma_f32_32x32x2_f32 v[124:139], v178, v17, 0
	v_mfma_f32_32x32x2_f32 v[146:161], v178, v12, 0
	v_mfma_f32_32x32x2_f32 v[162:177], v178, v13, 0
	v_mfma_f32_32x32x2_f32 v[108:123], v179, v18, v[108:123]
	v_mfma_f32_32x32x2_f32 v[124:139], v179, v19, v[124:139]
	v_mfma_f32_32x32x2_f32 v[146:161], v179, v14, v[146:161]
	v_mfma_f32_32x32x2_f32 v[162:177], v179, v15, v[162:177]
	v_mfma_f32_32x32x2_f32 v[108:123], v180, v20, v[108:123]
	v_mfma_f32_32x32x2_f32 v[124:139], v180, v21, v[124:139]
	v_mfma_f32_32x32x2_f32 v[146:161], v180, v8, v[146:161]
	v_mfma_f32_32x32x2_f32 v[162:177], v180, v9, v[162:177]
	v_mfma_f32_32x32x2_f32 v[108:123], v181, v22, v[108:123]
	v_mfma_f32_32x32x2_f32 v[124:139], v181, v23, v[124:139]
	v_mfma_f32_32x32x2_f32 v[146:161], v181, v10, v[146:161]
	v_mfma_f32_32x32x2_f32 v[162:177], v181, v11, v[162:177]
	v_mfma_f32_32x32x2_f32 v[108:123], v182, v24, v[108:123]
	v_mfma_f32_32x32x2_f32 v[124:139], v182, v25, v[124:139]
	v_mfma_f32_32x32x2_f32 v[146:161], v182, v4, v[146:161]
	v_mfma_f32_32x32x2_f32 v[162:177], v182, v5, v[162:177]
	v_mfma_f32_32x32x2_f32 v[108:123], v183, v26, v[108:123]
	v_mfma_f32_32x32x2_f32 v[124:139], v183, v27, v[124:139]
	v_mfma_f32_32x32x2_f32 v[146:161], v183, v6, v[146:161]
	v_mfma_f32_32x32x2_f32 v[162:177], v183, v7, v[162:177]
	v_mfma_f32_32x32x2_f32 v[108:123], v184, v28, v[108:123]
	v_mfma_f32_32x32x2_f32 v[124:139], v184, v29, v[124:139]
	v_mfma_f32_32x32x2_f32 v[146:161], v184, v0, v[146:161]
	v_mfma_f32_32x32x2_f32 v[162:177], v184, v1, v[162:177]
	v_mfma_f32_32x32x2_f32 v[108:123], v185, v30, v[108:123]
	v_mfma_f32_32x32x2_f32 v[124:139], v185, v31, v[124:139]
	v_mfma_f32_32x32x2_f32 v[146:161], v185, v2, v[146:161]
	v_mfma_f32_32x32x2_f32 v[162:177], v185, v3, v[162:177]
	s_nop 7
	s_nop 7
	s_nop 7
	v_permlane32_swap_b32_e32 v108, v146
	v_permlane32_swap_b32_e32 v124, v162
	v_permlane32_swap_b32_e32 v109, v147
	v_permlane32_swap_b32_e32 v125, v163
	v_permlane32_swap_b32_e32 v110, v148
	v_permlane32_swap_b32_e32 v126, v164
	v_permlane32_swap_b32_e32 v111, v149
	v_permlane32_swap_b32_e32 v127, v165
	v_permlane32_swap_b32_e32 v112, v150
	v_permlane32_swap_b32_e32 v128, v166
	v_permlane32_swap_b32_e32 v113, v151
	v_permlane32_swap_b32_e32 v129, v167
	v_permlane32_swap_b32_e32 v114, v152
	v_permlane32_swap_b32_e32 v130, v168
	v_permlane32_swap_b32_e32 v115, v153
	v_permlane32_swap_b32_e32 v131, v169
	v_permlane32_swap_b32_e32 v116, v154
	v_permlane32_swap_b32_e32 v132, v170
	v_permlane32_swap_b32_e32 v117, v155
	v_permlane32_swap_b32_e32 v133, v171
	v_permlane32_swap_b32_e32 v118, v156
	v_permlane32_swap_b32_e32 v134, v172
	v_permlane32_swap_b32_e32 v119, v157
	v_permlane32_swap_b32_e32 v135, v173
	v_permlane32_swap_b32_e32 v120, v158
	v_permlane32_swap_b32_e32 v136, v174
	v_permlane32_swap_b32_e32 v121, v159
	v_permlane32_swap_b32_e32 v137, v175
	v_permlane32_swap_b32_e32 v122, v160
	v_permlane32_swap_b32_e32 v138, v176
	v_permlane32_swap_b32_e32 v123, v161
	v_permlane32_swap_b32_e32 v139, v177
	v_mul_f32_e32 v188, v34, v37
	v_mul_f32_e32 v189, v35, v37
	v_fma_f32 v190, v32, v36, -v188
	v_fma_f32 v191, v33, v36, v189
	v_add_f32_e32 v36, v190, v108
	v_add_f32_e32 v37, v191, v124
	v_mul_f32_e32 v188, v34, v37
	v_mul_f32_e32 v189, v35, v37
	v_fma_f32 v190, v32, v36, -v188
	v_fma_f32 v191, v33, v36, v189
	v_add_f32_e32 v36, v190, v109
	v_add_f32_e32 v37, v191, v125
	v_mul_f32_e32 v188, v34, v37
	v_mul_f32_e32 v189, v35, v37
	v_fma_f32 v190, v32, v36, -v188
	v_fma_f32 v191, v33, v36, v189
	v_add_f32_e32 v36, v190, v110
	v_add_f32_e32 v37, v191, v126
	v_mul_f32_e32 v188, v34, v37
	v_mul_f32_e32 v189, v35, v37
	v_fma_f32 v190, v32, v36, -v188
	v_fma_f32 v191, v33, v36, v189
	v_add_f32_e32 v36, v190, v111
	v_add_f32_e32 v37, v191, v127
	v_mul_f32_e32 v188, v34, v37
	v_mul_f32_e32 v189, v35, v37
	v_fma_f32 v190, v32, v36, -v188
	v_fma_f32 v191, v33, v36, v189
	v_add_f32_e32 v36, v190, v146
	v_add_f32_e32 v37, v191, v162
	v_mul_f32_e32 v188, v34, v37
	v_mul_f32_e32 v189, v35, v37
	v_fma_f32 v190, v32, v36, -v188
	v_fma_f32 v191, v33, v36, v189
	v_add_f32_e32 v36, v190, v147
	v_add_f32_e32 v37, v191, v163
	v_mul_f32_e32 v188, v34, v37
	v_mul_f32_e32 v189, v35, v37
	v_fma_f32 v190, v32, v36, -v188
	v_fma_f32 v191, v33, v36, v189
	v_add_f32_e32 v36, v190, v148
	v_add_f32_e32 v37, v191, v164
	v_mul_f32_e32 v188, v34, v37
	v_mul_f32_e32 v189, v35, v37
	v_fma_f32 v190, v32, v36, -v188
	v_fma_f32 v191, v33, v36, v189
	v_add_f32_e32 v36, v190, v149
	v_add_f32_e32 v37, v191, v165
	v_mul_f32_e32 v188, v34, v37
	v_mul_f32_e32 v189, v35, v37
; __device__ __forceinline__ void s5_pass1(const Params& p, int layer, int task, char* sm) {
;     ...
;   for (int l = 0; l < 128; l++) S5_STEP(sU + l * 16)
	v_fma_f32 v190, v32, v36, -v188
	v_fma_f32 v191, v33, v36, v189
	v_add_f32_e32 v36, v190, v112
	v_add_f32_e32 v37, v191, v128
	v_mul_f32_e32 v188, v34, v37
	v_mul_f32_e32 v189, v35, v37
	v_fma_f32 v190, v32, v36, -v188
	v_fma_f32 v191, v33, v36, v189
	v_add_f32_e32 v36, v190, v113
	v_add_f32_e32 v37, v191, v129
	v_mul_f32_e32 v188, v34, v37
	v_mul_f32_e32 v189, v35, v37
	v_fma_f32 v190, v32, v36, -v188
	v_fma_f32 v191, v33, v36, v189
	v_add_f32_e32 v36, v190, v114
	v_add_f32_e32 v37, v191, v130
	v_mul_f32_e32 v188, v34, v37
	v_mul_f32_e32 v189, v35, v37
	v_fma_f32 v190, v32, v36, -v188
	v_fma_f32 v191, v33, v36, v189
	v_add_f32_e32 v36, v190, v115
	v_add_f32_e32 v37, v191, v131
	v_mul_f32_e32 v188, v34, v37
	v_mul_f32_e32 v189, v35, v37
	v_fma_f32 v190, v32, v36, -v188
	v_fma_f32 v191, v33, v36, v189
	v_add_f32_e32 v36, v190, v150
	v_add_f32_e32 v37, v191, v166
	v_mul_f32_e32 v188, v34, v37
	v_mul_f32_e32 v189, v35, v37
	v_fma_f32 v190, v32, v36, -v188
	v_fma_f32 v191, v33, v36, v189
	v_add_f32_e32 v36, v190, v151
	v_add_f32_e32 v37, v191, v167
	v_mul_f32_e32 v188, v34, v37
	v_mul_f32_e32 v189, v35, v37
	v_fma_f32 v190, v32, v36, -v188
	v_fma_f32 v191, v33, v36, v189
	v_add_f32_e32 v36, v190, v152
	v_add_f32_e32 v37, v191, v168
	v_mul_f32_e32 v188, v34, v37
	v_mul_f32_e32 v189, v35, v37
	v_fma_f32 v190, v32, v36, -v188
	v_fma_f32 v191, v33, v36, v189
	v_add_f32_e32 v36, v190, v153
	v_add_f32_e32 v37, v191, v169
	v_mul_f32_e32 v188, v34, v37
	v_mul_f32_e32 v189, v35, v37
	v_fma_f32 v190, v32, v36, -v188
	v_fma_f32 v191, v33, v36, v189
	v_add_f32_e32 v36, v190, v116
	v_add_f32_e32 v37, v191, v132
	v_mul_f32_e32 v188, v34, v37
	v_mul_f32_e32 v189, v35, v37
	v_fma_f32 v190, v32, v36, -v188
	v_fma_f32 v191, v33, v36, v189
	v_add_f32_e32 v36, v190, v117
	v_add_f32_e32 v37, v191, v133
	v_mul_f32_e32 v188, v34, v37
	v_mul_f32_e32 v189, v35, v37
	v_fma_f32 v190, v32, v36, -v188
	v_fma_f32 v191, v33, v36, v189
	v_add_f32_e32 v36, v190, v118
	v_add_f32_e32 v37, v191, v134
	v_mul_f32_e32 v188, v34, v37
	v_mul_f32_e32 v189, v35, v37
	v_fma_f32 v190, v32, v36, -v188
	v_fma_f32 v191, v33, v36, v189
	v_add_f32_e32 v36, v190, v119
	v_add_f32_e32 v37, v191, v135
	v_mul_f32_e32 v188, v34, v37
	v_mul_f32_e32 v189, v35, v37
	v_fma_f32 v190, v32, v36, -v188
	v_fma_f32 v191, v33, v36, v189
	v_add_f32_e32 v36, v190, v154
	v_add_f32_e32 v37, v191, v170
	v_mul_f32_e32 v188, v34, v37
	v_mul_f32_e32 v189, v35, v37
	v_fma_f32 v190, v32, v36, -v188
	v_fma_f32 v191, v33, v36, v189
	v_add_f32_e32 v36, v190, v155
	v_add_f32_e32 v37, v191, v171
	v_mul_f32_e32 v188, v34, v37
	v_mul_f32_e32 v189, v35, v37
	v_fma_f32 v190, v32, v36, -v188
	v_fma_f32 v191, v33, v36, v189
	v_add_f32_e32 v36, v190, v156
	v_add_f32_e32 v37, v191, v172
	v_mul_f32_e32 v188, v34, v37
	v_mul_f32_e32 v189, v35, v37
	v_fma_f32 v190, v32, v36, -v188
	v_fma_f32 v191, v33, v36, v189
	v_add_f32_e32 v36, v190, v157
	v_add_f32_e32 v37, v191, v173
	v_mul_f32_e32 v188, v34, v37
	v_mul_f32_e32 v189, v35, v37
	v_fma_f32 v190, v32, v36, -v188
	v_fma_f32 v191, v33, v36, v189
	v_add_f32_e32 v36, v190, v120
	v_add_f32_e32 v37, v191, v136
	v_mul_f32_e32 v188, v34, v37
	v_mul_f32_e32 v189, v35, v37
	v_fma_f32 v190, v32, v36, -v188
	v_fma_f32 v191, v33, v36, v189
	v_add_f32_e32 v36, v190, v121
	v_add_f32_e32 v37, v191, v137
	v_mul_f32_e32 v188, v34, v37
	v_mul_f32_e32 v189, v35, v37
	v_fma_f32 v190, v32, v36, -v188
	v_fma_f32 v191, v33, v36, v189
	v_add_f32_e32 v36, v190, v122
	v_add_f32_e32 v37, v191, v138
	v_mul_f32_e32 v188, v34, v37
	v_mul_f32_e32 v189, v35, v37
	v_fma_f32 v190, v32, v36, -v188
	v_fma_f32 v191, v33, v36, v189
	v_add_f32_e32 v36, v190, v123
	v_add_f32_e32 v37, v191, v139
	v_mul_f32_e32 v188, v34, v37
	v_mul_f32_e32 v189, v35, v37
	v_fma_f32 v190, v32, v36, -v188
	v_fma_f32 v191, v33, v36, v189
	v_add_f32_e32 v36, v190, v158
	v_add_f32_e32 v37, v191, v174
	v_mul_f32_e32 v188, v34, v37
	v_mul_f32_e32 v189, v35, v37
	v_fma_f32 v190, v32, v36, -v188
	v_fma_f32 v191, v33, v36, v189
	v_add_f32_e32 v36, v190, v159
	v_add_f32_e32 v37, v191, v175
	v_mul_f32_e32 v188, v34, v37
	v_mul_f32_e32 v189, v35, v37
	v_fma_f32 v190, v32, v36, -v188
	v_fma_f32 v191, v33, v36, v189
	v_add_f32_e32 v36, v190, v160
	v_add_f32_e32 v37, v191, v176
	v_mul_f32_e32 v188, v34, v37
	v_mul_f32_e32 v189, v35, v37
	v_fma_f32 v190, v32, v36, -v188
	v_fma_f32 v191, v33, v36, v189
	v_add_f32_e32 v36, v190, v161
	v_add_f32_e32 v37, v191, v177
	ds_read2_b32 v[178:179], v186 offset0:0 offset1:2
	ds_read2_b32 v[180:181], v186 offset0:4 offset1:6
	ds_read2_b32 v[182:183], v186 offset0:8 offset1:10
	ds_read2_b32 v[184:185], v186 offset0:12 offset1:14
	s_waitcnt lgkmcnt(0)
; __device__ __forceinline__ void s5_pass1(const Params& p, int layer, int task, char* sm) {
;     ...
;   for (int l = 0; l < 128; l++) S5_STEP(sU + l * 16)
	v_add_u32_e32 v186, 0x800, v186
	v_mfma_f32_32x32x2_f32 v[108:123], v178, v16, 0
	v_mfma_f32_32x32x2_f32 v[124:139], v178, v17, 0
	v_mfma_f32_32x32x2_f32 v[146:161], v178, v12, 0
	v_mfma_f32_32x32x2_f32 v[162:177], v178, v13, 0
	v_mfma_f32_32x32x2_f32 v[108:123], v179, v18, v[108:123]
	v_mfma_f32_32x32x2_f32 v[124:139], v179, v19, v[124:139]
	v_mfma_f32_32x32x2_f32 v[146:161], v179, v14, v[146:161]
	v_mfma_f32_32x32x2_f32 v[162:177], v179, v15, v[162:177]
	v_mfma_f32_32x32x2_f32 v[108:123], v180, v20, v[108:123]
	v_mfma_f32_32x32x2_f32 v[124:139], v180, v21, v[124:139]
	v_mfma_f32_32x32x2_f32 v[146:161], v180, v8, v[146:161]
	v_mfma_f32_32x32x2_f32 v[162:177], v180, v9, v[162:177]
	v_mfma_f32_32x32x2_f32 v[108:123], v181, v22, v[108:123]
	v_mfma_f32_32x32x2_f32 v[124:139], v181, v23, v[124:139]
	v_mfma_f32_32x32x2_f32 v[146:161], v181, v10, v[146:161]
	v_mfma_f32_32x32x2_f32 v[162:177], v181, v11, v[162:177]
	v_mfma_f32_32x32x2_f32 v[108:123], v182, v24, v[108:123]
	v_mfma_f32_32x32x2_f32 v[124:139], v182, v25, v[124:139]
	v_mfma_f32_32x32x2_f32 v[146:161], v182, v4, v[146:161]
	v_mfma_f32_32x32x2_f32 v[162:177], v182, v5, v[162:177]
	v_mfma_f32_32x32x2_f32 v[108:123], v183, v26, v[108:123]
	v_mfma_f32_32x32x2_f32 v[124:139], v183, v27, v[124:139]
	v_mfma_f32_32x32x2_f32 v[146:161], v183, v6, v[146:161]
	v_mfma_f32_32x32x2_f32 v[162:177], v183, v7, v[162:177]
	v_mfma_f32_32x32x2_f32 v[108:123], v184, v28, v[108:123]
	v_mfma_f32_32x32x2_f32 v[124:139], v184, v29, v[124:139]
	v_mfma_f32_32x32x2_f32 v[146:161], v184, v0, v[146:161]
	v_mfma_f32_32x32x2_f32 v[162:177], v184, v1, v[162:177]
	v_mfma_f32_32x32x2_f32 v[108:123], v185, v30, v[108:123]
	v_mfma_f32_32x32x2_f32 v[124:139], v185, v31, v[124:139]
	v_mfma_f32_32x32x2_f32 v[146:161], v185, v2, v[146:161]
	v_mfma_f32_32x32x2_f32 v[162:177], v185, v3, v[162:177]
	s_nop 7
	s_nop 7
	s_nop 7
	v_permlane32_swap_b32_e32 v108, v146
	v_permlane32_swap_b32_e32 v124, v162
	v_permlane32_swap_b32_e32 v109, v147
	v_permlane32_swap_b32_e32 v125, v163
	v_permlane32_swap_b32_e32 v110, v148
	v_permlane32_swap_b32_e32 v126, v164
	v_permlane32_swap_b32_e32 v111, v149
	v_permlane32_swap_b32_e32 v127, v165
	v_permlane32_swap_b32_e32 v112, v150
	v_permlane32_swap_b32_e32 v128, v166
	v_permlane32_swap_b32_e32 v113, v151
	v_permlane32_swap_b32_e32 v129, v167
	v_permlane32_swap_b32_e32 v114, v152
	v_permlane32_swap_b32_e32 v130, v168
	v_permlane32_swap_b32_e32 v115, v153
	v_permlane32_swap_b32_e32 v131, v169
	v_permlane32_swap_b32_e32 v116, v154
	v_permlane32_swap_b32_e32 v132, v170
	v_permlane32_swap_b32_e32 v117, v155
	v_permlane32_swap_b32_e32 v133, v171
	v_permlane32_swap_b32_e32 v118, v156
	v_permlane32_swap_b32_e32 v134, v172
	v_permlane32_swap_b32_e32 v119, v157
	v_permlane32_swap_b32_e32 v135, v173
	v_permlane32_swap_b32_e32 v120, v158
	v_permlane32_swap_b32_e32 v136, v174
	v_permlane32_swap_b32_e32 v121, v159
	v_permlane32_swap_b32_e32 v137, v175
	v_permlane32_swap_b32_e32 v122, v160
	v_permlane32_swap_b32_e32 v138, v176
	v_permlane32_swap_b32_e32 v123, v161
	v_permlane32_swap_b32_e32 v139, v177
	v_mul_f32_e32 v188, v34, v37
	v_mul_f32_e32 v189, v35, v37
	v_fma_f32 v190, v32, v36, -v188
	v_fma_f32 v191, v33, v36, v189
	v_add_f32_e32 v36, v190, v108
	v_add_f32_e32 v37, v191, v124
	v_mul_f32_e32 v188, v34, v37
	v_mul_f32_e32 v189, v35, v37
	v_fma_f32 v190, v32, v36, -v188
	v_fma_f32 v191, v33, v36, v189
	v_add_f32_e32 v36, v190, v109
	v_add_f32_e32 v37, v191, v125
	v_mul_f32_e32 v188, v34, v37
	v_mul_f32_e32 v189, v35, v37
	v_fma_f32 v190, v32, v36, -v188
	v_fma_f32 v191, v33, v36, v189
	v_add_f32_e32 v36, v190, v110
	v_add_f32_e32 v37, v191, v126
	v_mul_f32_e32 v188, v34, v37
	v_mul_f32_e32 v189, v35, v37
	v_fma_f32 v190, v32, v36, -v188
	v_fma_f32 v191, v33, v36, v189
	v_add_f32_e32 v36, v190, v111
	v_add_f32_e32 v37, v191, v127
	v_mul_f32_e32 v188, v34, v37
	v_mul_f32_e32 v189, v35, v37
	v_fma_f32 v190, v32, v36, -v188
	v_fma_f32 v191, v33, v36, v189
	v_add_f32_e32 v36, v190, v146
	v_add_f32_e32 v37, v191, v162
	v_mul_f32_e32 v188, v34, v37
	v_mul_f32_e32 v189, v35, v37
	v_fma_f32 v190, v32, v36, -v188
	v_fma_f32 v191, v33, v36, v189
	v_add_f32_e32 v36, v190, v147
	v_add_f32_e32 v37, v191, v163
	v_mul_f32_e32 v188, v34, v37
	v_mul_f32_e32 v189, v35, v37
	v_fma_f32 v190, v32, v36, -v188
	v_fma_f32 v191, v33, v36, v189
	v_add_f32_e32 v36, v190, v148
	v_add_f32_e32 v37, v191, v164
	v_mul_f32_e32 v188, v34, v37
	v_mul_f32_e32 v189, v35, v37
	v_fma_f32 v190, v32, v36, -v188
	v_fma_f32 v191, v33, v36, v189
	v_add_f32_e32 v36, v190, v149
	v_add_f32_e32 v37, v191, v165
	v_mul_f32_e32 v188, v34, v37
	v_mul_f32_e32 v189, v35, v37
	v_fma_f32 v190, v32, v36, -v188
	v_fma_f32 v191, v33, v36, v189
	v_add_f32_e32 v36, v190, v112
	v_add_f32_e32 v37, v191, v128
	v_mul_f32_e32 v188, v34, v37
	v_mul_f32_e32 v189, v35, v37
	v_fma_f32 v190, v32, v36, -v188
	v_fma_f32 v191, v33, v36, v189
	v_add_f32_e32 v36, v190, v113
	v_add_f32_e32 v37, v191, v129
	v_mul_f32_e32 v188, v34, v37
	v_mul_f32_e32 v189, v35, v37
	v_fma_f32 v190, v32, v36, -v188
	v_fma_f32 v191, v33, v36, v189
	v_add_f32_e32 v36, v190, v114
	v_add_f32_e32 v37, v191, v130
	v_mul_f32_e32 v188, v34, v37
	v_mul_f32_e32 v189, v35, v37
	v_fma_f32 v190, v32, v36, -v188
	v_fma_f32 v191, v33, v36, v189
	v_add_f32_e32 v36, v190, v115
	v_add_f32_e32 v37, v191, v131
	v_mul_f32_e32 v188, v34, v37
	v_mul_f32_e32 v189, v35, v37
	v_fma_f32 v190, v32, v36, -v188
	v_fma_f32 v191, v33, v36, v189
	v_add_f32_e32 v36, v190, v150
	v_add_f32_e32 v37, v191, v166
	v_mul_f32_e32 v188, v34, v37
	v_mul_f32_e32 v189, v35, v37
	v_fma_f32 v190, v32, v36, -v188
	v_fma_f32 v191, v33, v36, v189
; __device__ __forceinline__ void s5_pass1(const Params& p, int layer, int task, char* sm) {
;     ...
;   for (int l = 0; l < 128; l++) S5_STEP(sU + l * 16)
	v_add_f32_e32 v36, v190, v151
	v_add_f32_e32 v37, v191, v167
	v_mul_f32_e32 v188, v34, v37
	v_mul_f32_e32 v189, v35, v37
	v_fma_f32 v190, v32, v36, -v188
	v_fma_f32 v191, v33, v36, v189
	v_add_f32_e32 v36, v190, v152
	v_add_f32_e32 v37, v191, v168
	v_mul_f32_e32 v188, v34, v37
	v_mul_f32_e32 v189, v35, v37
	v_fma_f32 v190, v32, v36, -v188
	v_fma_f32 v191, v33, v36, v189
	v_add_f32_e32 v36, v190, v153
	v_add_f32_e32 v37, v191, v169
	v_mul_f32_e32 v188, v34, v37
	v_mul_f32_e32 v189, v35, v37
	v_fma_f32 v190, v32, v36, -v188
	v_fma_f32 v191, v33, v36, v189
	v_add_f32_e32 v36, v190, v116
	v_add_f32_e32 v37, v191, v132
	v_mul_f32_e32 v188, v34, v37
	v_mul_f32_e32 v189, v35, v37
	v_fma_f32 v190, v32, v36, -v188
	v_fma_f32 v191, v33, v36, v189
	v_add_f32_e32 v36, v190, v117
	v_add_f32_e32 v37, v191, v133
	v_mul_f32_e32 v188, v34, v37
	v_mul_f32_e32 v189, v35, v37
	v_fma_f32 v190, v32, v36, -v188
	v_fma_f32 v191, v33, v36, v189
	v_add_f32_e32 v36, v190, v118
	v_add_f32_e32 v37, v191, v134
	v_mul_f32_e32 v188, v34, v37
	v_mul_f32_e32 v189, v35, v37
	v_fma_f32 v190, v32, v36, -v188
	v_fma_f32 v191, v33, v36, v189
	v_add_f32_e32 v36, v190, v119
	v_add_f32_e32 v37, v191, v135
	v_mul_f32_e32 v188, v34, v37
	v_mul_f32_e32 v189, v35, v37
	v_fma_f32 v190, v32, v36, -v188
	v_fma_f32 v191, v33, v36, v189
	v_add_f32_e32 v36, v190, v154
	v_add_f32_e32 v37, v191, v170
	v_mul_f32_e32 v188, v34, v37
	v_mul_f32_e32 v189, v35, v37
	v_fma_f32 v190, v32, v36, -v188
	v_fma_f32 v191, v33, v36, v189
	v_add_f32_e32 v36, v190, v155
	v_add_f32_e32 v37, v191, v171
	v_mul_f32_e32 v188, v34, v37
	v_mul_f32_e32 v189, v35, v37
	v_fma_f32 v190, v32, v36, -v188
	v_fma_f32 v191, v33, v36, v189
	v_add_f32_e32 v36, v190, v156
	v_add_f32_e32 v37, v191, v172
	v_mul_f32_e32 v188, v34, v37
	v_mul_f32_e32 v189, v35, v37
	v_fma_f32 v190, v32, v36, -v188
	v_fma_f32 v191, v33, v36, v189
	v_add_f32_e32 v36, v190, v157
	v_add_f32_e32 v37, v191, v173
	v_mul_f32_e32 v188, v34, v37
	v_mul_f32_e32 v189, v35, v37
	v_fma_f32 v190, v32, v36, -v188
	v_fma_f32 v191, v33, v36, v189
	v_add_f32_e32 v36, v190, v120
	v_add_f32_e32 v37, v191, v136
	v_mul_f32_e32 v188, v34, v37
	v_mul_f32_e32 v189, v35, v37
	v_fma_f32 v190, v32, v36, -v188
	v_fma_f32 v191, v33, v36, v189
	v_add_f32_e32 v36, v190, v121
	v_add_f32_e32 v37, v191, v137
	v_mul_f32_e32 v188, v34, v37
	v_mul_f32_e32 v189, v35, v37
	v_fma_f32 v190, v32, v36, -v188
	v_fma_f32 v191, v33, v36, v189
	v_add_f32_e32 v36, v190, v122
	v_add_f32_e32 v37, v191, v138
	v_mul_f32_e32 v188, v34, v37
	v_mul_f32_e32 v189, v35, v37
	v_fma_f32 v190, v32, v36, -v188
	v_fma_f32 v191, v33, v36, v189
	v_add_f32_e32 v36, v190, v123
	v_add_f32_e32 v37, v191, v139
	v_mul_f32_e32 v188, v34, v37
	v_mul_f32_e32 v189, v35, v37
	v_fma_f32 v190, v32, v36, -v188
	v_fma_f32 v191, v33, v36, v189
	v_add_f32_e32 v36, v190, v158
	v_add_f32_e32 v37, v191, v174
	v_mul_f32_e32 v188, v34, v37
	v_mul_f32_e32 v189, v35, v37
	v_fma_f32 v190, v32, v36, -v188
	v_fma_f32 v191, v33, v36, v189
	v_add_f32_e32 v36, v190, v159
	v_add_f32_e32 v37, v191, v175
	v_mul_f32_e32 v188, v34, v37
	v_mul_f32_e32 v189, v35, v37
	v_fma_f32 v190, v32, v36, -v188
	v_fma_f32 v191, v33, v36, v189
	v_add_f32_e32 v36, v190, v160
	v_add_f32_e32 v37, v191, v176
	v_mul_f32_e32 v188, v34, v37
	v_mul_f32_e32 v189, v35, v37
	v_fma_f32 v190, v32, v36, -v188
	v_fma_f32 v191, v33, v36, v189
	v_add_f32_e32 v36, v190, v161
	v_add_f32_e32 v37, v191, v177
	ds_read2_b32 v[178:179], v186 offset0:0 offset1:2
	ds_read2_b32 v[180:181], v186 offset0:4 offset1:6
	ds_read2_b32 v[182:183], v186 offset0:8 offset1:10
	ds_read2_b32 v[184:185], v186 offset0:12 offset1:14
	s_waitcnt lgkmcnt(0)
	v_add_u32_e32 v186, 0x800, v186
	v_mfma_f32_32x32x2_f32 v[108:123], v178, v16, 0
	v_mfma_f32_32x32x2_f32 v[124:139], v178, v17, 0
	v_mfma_f32_32x32x2_f32 v[146:161], v178, v12, 0
	v_mfma_f32_32x32x2_f32 v[162:177], v178, v13, 0
	v_mfma_f32_32x32x2_f32 v[108:123], v179, v18, v[108:123]
	v_mfma_f32_32x32x2_f32 v[124:139], v179, v19, v[124:139]
	v_mfma_f32_32x32x2_f32 v[146:161], v179, v14, v[146:161]
	v_mfma_f32_32x32x2_f32 v[162:177], v179, v15, v[162:177]
	v_mfma_f32_32x32x2_f32 v[108:123], v180, v20, v[108:123]
	v_mfma_f32_32x32x2_f32 v[124:139], v180, v21, v[124:139]
	v_mfma_f32_32x32x2_f32 v[146:161], v180, v8, v[146:161]
	v_mfma_f32_32x32x2_f32 v[162:177], v180, v9, v[162:177]
	v_mfma_f32_32x32x2_f32 v[108:123], v181, v22, v[108:123]
	v_mfma_f32_32x32x2_f32 v[124:139], v181, v23, v[124:139]
	v_mfma_f32_32x32x2_f32 v[146:161], v181, v10, v[146:161]
	v_mfma_f32_32x32x2_f32 v[162:177], v181, v11, v[162:177]
	v_mfma_f32_32x32x2_f32 v[108:123], v182, v24, v[108:123]
	v_mfma_f32_32x32x2_f32 v[124:139], v182, v25, v[124:139]
	v_mfma_f32_32x32x2_f32 v[146:161], v182, v4, v[146:161]
	v_mfma_f32_32x32x2_f32 v[162:177], v182, v5, v[162:177]
	v_mfma_f32_32x32x2_f32 v[108:123], v183, v26, v[108:123]
	v_mfma_f32_32x32x2_f32 v[124:139], v183, v27, v[124:139]
	v_mfma_f32_32x32x2_f32 v[146:161], v183, v6, v[146:161]
	v_mfma_f32_32x32x2_f32 v[162:177], v183, v7, v[162:177]
	v_mfma_f32_32x32x2_f32 v[108:123], v184, v28, v[108:123]
	v_mfma_f32_32x32x2_f32 v[124:139], v184, v29, v[124:139]
	v_mfma_f32_32x32x2_f32 v[146:161], v184, v0, v[146:161]
	v_mfma_f32_32x32x2_f32 v[162:177], v184, v1, v[162:177]
	v_mfma_f32_32x32x2_f32 v[108:123], v185, v30, v[108:123]
	v_mfma_f32_32x32x2_f32 v[124:139], v185, v31, v[124:139]
	v_mfma_f32_32x32x2_f32 v[146:161], v185, v2, v[146:161]
	v_mfma_f32_32x32x2_f32 v[162:177], v185, v3, v[162:177]
	s_nop 7
	s_nop 7
	s_nop 7
	v_permlane32_swap_b32_e32 v108, v146
	v_permlane32_swap_b32_e32 v124, v162
	v_permlane32_swap_b32_e32 v109, v147
; __device__ __forceinline__ void s5_pass1(const Params& p, int layer, int task, char* sm) {
;     ...
;   for (int l = 0; l < 128; l++) S5_STEP(sU + l * 16)
	v_permlane32_swap_b32_e32 v125, v163
	v_permlane32_swap_b32_e32 v110, v148
	v_permlane32_swap_b32_e32 v126, v164
	v_permlane32_swap_b32_e32 v111, v149
	v_permlane32_swap_b32_e32 v127, v165
	v_permlane32_swap_b32_e32 v112, v150
	v_permlane32_swap_b32_e32 v128, v166
	v_permlane32_swap_b32_e32 v113, v151
	v_permlane32_swap_b32_e32 v129, v167
	v_permlane32_swap_b32_e32 v114, v152
	v_permlane32_swap_b32_e32 v130, v168
	v_permlane32_swap_b32_e32 v115, v153
	v_permlane32_swap_b32_e32 v131, v169
	v_permlane32_swap_b32_e32 v116, v154
	v_permlane32_swap_b32_e32 v132, v170
	v_permlane32_swap_b32_e32 v117, v155
	v_permlane32_swap_b32_e32 v133, v171
	v_permlane32_swap_b32_e32 v118, v156
	v_permlane32_swap_b32_e32 v134, v172
	v_permlane32_swap_b32_e32 v119, v157
	v_permlane32_swap_b32_e32 v135, v173
	v_permlane32_swap_b32_e32 v120, v158
	v_permlane32_swap_b32_e32 v136, v174
	v_permlane32_swap_b32_e32 v121, v159
	v_permlane32_swap_b32_e32 v137, v175
	v_permlane32_swap_b32_e32 v122, v160
	v_permlane32_swap_b32_e32 v138, v176
	v_permlane32_swap_b32_e32 v123, v161
	v_permlane32_swap_b32_e32 v139, v177
	v_mul_f32_e32 v188, v34, v37
	v_mul_f32_e32 v189, v35, v37
	v_fma_f32 v190, v32, v36, -v188
	v_fma_f32 v191, v33, v36, v189
	v_add_f32_e32 v36, v190, v108
	v_add_f32_e32 v37, v191, v124
	v_mul_f32_e32 v188, v34, v37
	v_mul_f32_e32 v189, v35, v37
	v_fma_f32 v190, v32, v36, -v188
	v_fma_f32 v191, v33, v36, v189
	v_add_f32_e32 v36, v190, v109
	v_add_f32_e32 v37, v191, v125
	v_mul_f32_e32 v188, v34, v37
	v_mul_f32_e32 v189, v35, v37
	v_fma_f32 v190, v32, v36, -v188
	v_fma_f32 v191, v33, v36, v189
	v_add_f32_e32 v36, v190, v110
	v_add_f32_e32 v37, v191, v126
	v_mul_f32_e32 v188, v34, v37
	v_mul_f32_e32 v189, v35, v37
	v_fma_f32 v190, v32, v36, -v188
	v_fma_f32 v191, v33, v36, v189
	v_add_f32_e32 v36, v190, v111
	v_add_f32_e32 v37, v191, v127
	v_mul_f32_e32 v188, v34, v37
	v_mul_f32_e32 v189, v35, v37
	v_fma_f32 v190, v32, v36, -v188
	v_fma_f32 v191, v33, v36, v189
	v_add_f32_e32 v36, v190, v146
	v_add_f32_e32 v37, v191, v162
	v_mul_f32_e32 v188, v34, v37
	v_mul_f32_e32 v189, v35, v37
	v_fma_f32 v190, v32, v36, -v188
	v_fma_f32 v191, v33, v36, v189
	v_add_f32_e32 v36, v190, v147
	v_add_f32_e32 v37, v191, v163
	v_mul_f32_e32 v188, v34, v37
	v_mul_f32_e32 v189, v35, v37
	v_fma_f32 v190, v32, v36, -v188
	v_fma_f32 v191, v33, v36, v189
	v_add_f32_e32 v36, v190, v148
	v_add_f32_e32 v37, v191, v164
	v_mul_f32_e32 v188, v34, v37
	v_mul_f32_e32 v189, v35, v37
	v_fma_f32 v190, v32, v36, -v188
	v_fma_f32 v191, v33, v36, v189
	v_add_f32_e32 v36, v190, v149
	v_add_f32_e32 v37, v191, v165
	v_mul_f32_e32 v188, v34, v37
	v_mul_f32_e32 v189, v35, v37
	v_fma_f32 v190, v32, v36, -v188
	v_fma_f32 v191, v33, v36, v189
	v_add_f32_e32 v36, v190, v112
	v_add_f32_e32 v37, v191, v128
	v_mul_f32_e32 v188, v34, v37
	v_mul_f32_e32 v189, v35, v37
	v_fma_f32 v190, v32, v36, -v188
	v_fma_f32 v191, v33, v36, v189
	v_add_f32_e32 v36, v190, v113
	v_add_f32_e32 v37, v191, v129
	v_mul_f32_e32 v188, v34, v37
	v_mul_f32_e32 v189, v35, v37
	v_fma_f32 v190, v32, v36, -v188
	v_fma_f32 v191, v33, v36, v189
	v_add_f32_e32 v36, v190, v114
	v_add_f32_e32 v37, v191, v130
	v_mul_f32_e32 v188, v34, v37
	v_mul_f32_e32 v189, v35, v37
	v_fma_f32 v190, v32, v36, -v188
	v_fma_f32 v191, v33, v36, v189
	v_add_f32_e32 v36, v190, v115
	v_add_f32_e32 v37, v191, v131
	v_mul_f32_e32 v188, v34, v37
	v_mul_f32_e32 v189, v35, v37
	v_fma_f32 v190, v32, v36, -v188
	v_fma_f32 v191, v33, v36, v189
	v_add_f32_e32 v36, v190, v150
	v_add_f32_e32 v37, v191, v166
	v_mul_f32_e32 v188, v34, v37
	v_mul_f32_e32 v189, v35, v37
	v_fma_f32 v190, v32, v36, -v188
	v_fma_f32 v191, v33, v36, v189
	v_add_f32_e32 v36, v190, v151
	v_add_f32_e32 v37, v191, v167
	v_mul_f32_e32 v188, v34, v37
	v_mul_f32_e32 v189, v35, v37
	v_fma_f32 v190, v32, v36, -v188
	v_fma_f32 v191, v33, v36, v189
	v_add_f32_e32 v36, v190, v152
	v_add_f32_e32 v37, v191, v168
	v_mul_f32_e32 v188, v34, v37
	v_mul_f32_e32 v189, v35, v37
	v_fma_f32 v190, v32, v36, -v188
	v_fma_f32 v191, v33, v36, v189
	v_add_f32_e32 v36, v190, v153
	v_add_f32_e32 v37, v191, v169
	v_mul_f32_e32 v188, v34, v37
	v_mul_f32_e32 v189, v35, v37
	v_fma_f32 v190, v32, v36, -v188
	v_fma_f32 v191, v33, v36, v189
	v_add_f32_e32 v36, v190, v116
	v_add_f32_e32 v37, v191, v132
	v_mul_f32_e32 v188, v34, v37
	v_mul_f32_e32 v189, v35, v37
	v_fma_f32 v190, v32, v36, -v188
	v_fma_f32 v191, v33, v36, v189
	v_add_f32_e32 v36, v190, v117
	v_add_f32_e32 v37, v191, v133
	v_mul_f32_e32 v188, v34, v37
	v_mul_f32_e32 v189, v35, v37
	v_fma_f32 v190, v32, v36, -v188
	v_fma_f32 v191, v33, v36, v189
	v_add_f32_e32 v36, v190, v118
	v_add_f32_e32 v37, v191, v134
	v_mul_f32_e32 v188, v34, v37
	v_mul_f32_e32 v189, v35, v37
	v_fma_f32 v190, v32, v36, -v188
	v_fma_f32 v191, v33, v36, v189
	v_add_f32_e32 v36, v190, v119
	v_add_f32_e32 v37, v191, v135
	v_mul_f32_e32 v188, v34, v37
	v_mul_f32_e32 v189, v35, v37
	v_fma_f32 v190, v32, v36, -v188
	v_fma_f32 v191, v33, v36, v189
	v_add_f32_e32 v36, v190, v154
	v_add_f32_e32 v37, v191, v170
	v_mul_f32_e32 v188, v34, v37
	v_mul_f32_e32 v189, v35, v37
	v_fma_f32 v190, v32, v36, -v188
	v_fma_f32 v191, v33, v36, v189
	v_add_f32_e32 v36, v190, v155
	v_add_f32_e32 v37, v191, v171
	v_mul_f32_e32 v188, v34, v37
	v_mul_f32_e32 v189, v35, v37
	v_fma_f32 v190, v32, v36, -v188
	v_fma_f32 v191, v33, v36, v189
	v_add_f32_e32 v36, v190, v156
	v_add_f32_e32 v37, v191, v172
	v_mul_f32_e32 v188, v34, v37
	v_mul_f32_e32 v189, v35, v37
	v_fma_f32 v190, v32, v36, -v188
	v_fma_f32 v191, v33, v36, v189
	v_add_f32_e32 v36, v190, v157
	v_add_f32_e32 v37, v191, v173
	v_mul_f32_e32 v188, v34, v37
	v_mul_f32_e32 v189, v35, v37
; __device__ __forceinline__ void s5_pass1(const Params& p, int layer, int task, char* sm) {
;     ...
;   for (int l = 0; l < 128; l++) S5_STEP(sU + l * 16)
	v_fma_f32 v190, v32, v36, -v188
	v_fma_f32 v191, v33, v36, v189
	v_add_f32_e32 v36, v190, v120
	v_add_f32_e32 v37, v191, v136
	v_mul_f32_e32 v188, v34, v37
	v_mul_f32_e32 v189, v35, v37
	v_fma_f32 v190, v32, v36, -v188
	v_fma_f32 v191, v33, v36, v189
	v_add_f32_e32 v36, v190, v121
	v_add_f32_e32 v37, v191, v137
	v_mul_f32_e32 v188, v34, v37
	v_mul_f32_e32 v189, v35, v37
	v_fma_f32 v190, v32, v36, -v188
	v_fma_f32 v191, v33, v36, v189
	v_add_f32_e32 v36, v190, v122
	v_add_f32_e32 v37, v191, v138
	v_mul_f32_e32 v188, v34, v37
	v_mul_f32_e32 v189, v35, v37
	v_fma_f32 v190, v32, v36, -v188
	v_fma_f32 v191, v33, v36, v189
	v_add_f32_e32 v36, v190, v123
	v_add_f32_e32 v37, v191, v139
	v_mul_f32_e32 v188, v34, v37
	v_mul_f32_e32 v189, v35, v37
	v_fma_f32 v190, v32, v36, -v188
	v_fma_f32 v191, v33, v36, v189
	v_add_f32_e32 v36, v190, v158
	v_add_f32_e32 v37, v191, v174
	v_mul_f32_e32 v188, v34, v37
	v_mul_f32_e32 v189, v35, v37
	v_fma_f32 v190, v32, v36, -v188
	v_fma_f32 v191, v33, v36, v189
	v_add_f32_e32 v36, v190, v159
	v_add_f32_e32 v37, v191, v175
	v_mul_f32_e32 v188, v34, v37
	v_mul_f32_e32 v189, v35, v37
	v_fma_f32 v190, v32, v36, -v188
	v_fma_f32 v191, v33, v36, v189
	v_add_f32_e32 v36, v190, v160
	v_add_f32_e32 v37, v191, v176
	v_mul_f32_e32 v188, v34, v37
	v_mul_f32_e32 v189, v35, v37
	v_fma_f32 v190, v32, v36, -v188
	v_fma_f32 v191, v33, v36, v189
	v_add_f32_e32 v36, v190, v161
	v_add_f32_e32 v37, v191, v177
	ds_read2_b32 v[178:179], v186 offset0:0 offset1:2
	ds_read2_b32 v[180:181], v186 offset0:4 offset1:6
	ds_read2_b32 v[182:183], v186 offset0:8 offset1:10
	ds_read2_b32 v[184:185], v186 offset0:12 offset1:14
	s_waitcnt lgkmcnt(0)
	v_mfma_f32_32x32x2_f32 v[108:123], v178, v16, 0
	v_mfma_f32_32x32x2_f32 v[124:139], v178, v17, 0
	v_mfma_f32_32x32x2_f32 v[146:161], v178, v12, 0
	v_mfma_f32_32x32x2_f32 v[162:177], v178, v13, 0
	v_mfma_f32_32x32x2_f32 v[108:123], v179, v18, v[108:123]
	v_mfma_f32_32x32x2_f32 v[124:139], v179, v19, v[124:139]
	v_mfma_f32_32x32x2_f32 v[146:161], v179, v14, v[146:161]
	v_mfma_f32_32x32x2_f32 v[162:177], v179, v15, v[162:177]
	v_mfma_f32_32x32x2_f32 v[108:123], v180, v20, v[108:123]
	v_mfma_f32_32x32x2_f32 v[124:139], v180, v21, v[124:139]
	v_mfma_f32_32x32x2_f32 v[146:161], v180, v8, v[146:161]
	v_mfma_f32_32x32x2_f32 v[162:177], v180, v9, v[162:177]
	v_mfma_f32_32x32x2_f32 v[108:123], v181, v22, v[108:123]
	v_mfma_f32_32x32x2_f32 v[124:139], v181, v23, v[124:139]
	v_mfma_f32_32x32x2_f32 v[146:161], v181, v10, v[146:161]
	v_mfma_f32_32x32x2_f32 v[162:177], v181, v11, v[162:177]
	v_mfma_f32_32x32x2_f32 v[108:123], v182, v24, v[108:123]
	v_mfma_f32_32x32x2_f32 v[124:139], v182, v25, v[124:139]
	v_mfma_f32_32x32x2_f32 v[146:161], v182, v4, v[146:161]
	v_mfma_f32_32x32x2_f32 v[162:177], v182, v5, v[162:177]
	v_mfma_f32_32x32x2_f32 v[108:123], v183, v26, v[108:123]
	v_mfma_f32_32x32x2_f32 v[124:139], v183, v27, v[124:139]
	v_mfma_f32_32x32x2_f32 v[146:161], v183, v6, v[146:161]
	v_mfma_f32_32x32x2_f32 v[162:177], v183, v7, v[162:177]
	v_mfma_f32_32x32x2_f32 v[108:123], v184, v28, v[108:123]
	v_mfma_f32_32x32x2_f32 v[124:139], v184, v29, v[124:139]
	v_mfma_f32_32x32x2_f32 v[146:161], v184, v0, v[146:161]
	v_mfma_f32_32x32x2_f32 v[162:177], v184, v1, v[162:177]
	v_mfma_f32_32x32x2_f32 v[108:123], v185, v30, v[108:123]
	v_mfma_f32_32x32x2_f32 v[124:139], v185, v31, v[124:139]
	v_mfma_f32_32x32x2_f32 v[146:161], v185, v2, v[146:161]
	v_mfma_f32_32x32x2_f32 v[162:177], v185, v3, v[162:177]
	s_nop 7
	s_nop 7
	s_nop 7
	v_permlane32_swap_b32_e32 v108, v146
	v_permlane32_swap_b32_e32 v124, v162
	v_permlane32_swap_b32_e32 v109, v147
	v_permlane32_swap_b32_e32 v125, v163
	v_permlane32_swap_b32_e32 v110, v148
	v_permlane32_swap_b32_e32 v126, v164
	v_permlane32_swap_b32_e32 v111, v149
	v_permlane32_swap_b32_e32 v127, v165
	v_permlane32_swap_b32_e32 v112, v150
	v_permlane32_swap_b32_e32 v128, v166
	v_permlane32_swap_b32_e32 v113, v151
	v_permlane32_swap_b32_e32 v129, v167
	v_permlane32_swap_b32_e32 v114, v152
	v_permlane32_swap_b32_e32 v130, v168
	v_permlane32_swap_b32_e32 v115, v153
	v_permlane32_swap_b32_e32 v131, v169
	v_permlane32_swap_b32_e32 v116, v154
	v_permlane32_swap_b32_e32 v132, v170
	v_permlane32_swap_b32_e32 v117, v155
	v_permlane32_swap_b32_e32 v133, v171
	v_permlane32_swap_b32_e32 v118, v156
	v_permlane32_swap_b32_e32 v134, v172
	v_permlane32_swap_b32_e32 v119, v157
	v_permlane32_swap_b32_e32 v135, v173
	v_permlane32_swap_b32_e32 v120, v158
	v_permlane32_swap_b32_e32 v136, v174
	v_permlane32_swap_b32_e32 v121, v159
	v_permlane32_swap_b32_e32 v137, v175
	v_permlane32_swap_b32_e32 v122, v160
	v_permlane32_swap_b32_e32 v138, v176
	v_permlane32_swap_b32_e32 v123, v161
	v_permlane32_swap_b32_e32 v139, v177
	v_mul_f32_e32 v188, v34, v37
	v_mul_f32_e32 v189, v35, v37
	v_fma_f32 v190, v32, v36, -v188
	v_fma_f32 v191, v33, v36, v189
	v_add_f32_e32 v36, v190, v108
	v_add_f32_e32 v37, v191, v124
	v_mul_f32_e32 v188, v34, v37
	v_mul_f32_e32 v189, v35, v37
	v_fma_f32 v190, v32, v36, -v188
	v_fma_f32 v191, v33, v36, v189
	v_add_f32_e32 v36, v190, v109
	v_add_f32_e32 v37, v191, v125
	v_mul_f32_e32 v188, v34, v37
	v_mul_f32_e32 v189, v35, v37
	v_fma_f32 v190, v32, v36, -v188
	v_fma_f32 v191, v33, v36, v189
	v_add_f32_e32 v36, v190, v110
	v_add_f32_e32 v37, v191, v126
	v_mul_f32_e32 v188, v34, v37
	v_mul_f32_e32 v189, v35, v37
	v_fma_f32 v190, v32, v36, -v188
	v_fma_f32 v191, v33, v36, v189
	v_add_f32_e32 v36, v190, v111
	v_add_f32_e32 v37, v191, v127
	v_mul_f32_e32 v188, v34, v37
	v_mul_f32_e32 v189, v35, v37
	v_fma_f32 v190, v32, v36, -v188
	v_fma_f32 v191, v33, v36, v189
; __device__ __forceinline__ void s5_pass1(const Params& p, int layer, int task, char* sm) {
;     ...
;   for (int l = 0; l < 128; l++) S5_STEP(sU + l * 16)
;   *(float2*)(p.END + (((size_t)(b * 128 + c) * 32 + g) * 64 + lane) * 2) = make_float2(sr, si);
	v_add_f32_e32 v36, v190, v146
	v_add_f32_e32 v37, v191, v162
	v_mul_f32_e32 v188, v34, v37
	v_mul_f32_e32 v189, v35, v37
	v_fma_f32 v190, v32, v36, -v188
	v_fma_f32 v191, v33, v36, v189
	v_add_f32_e32 v36, v190, v147
	v_add_f32_e32 v37, v191, v163
	v_mul_f32_e32 v188, v34, v37
	v_mul_f32_e32 v189, v35, v37
	v_fma_f32 v190, v32, v36, -v188
	v_fma_f32 v191, v33, v36, v189
	v_add_f32_e32 v36, v190, v148
	v_add_f32_e32 v37, v191, v164
	v_mul_f32_e32 v188, v34, v37
	v_mul_f32_e32 v189, v35, v37
	v_fma_f32 v190, v32, v36, -v188
	v_fma_f32 v191, v33, v36, v189
	v_add_f32_e32 v36, v190, v149
	v_add_f32_e32 v37, v191, v165
	v_mul_f32_e32 v188, v34, v37
	v_mul_f32_e32 v189, v35, v37
	v_fma_f32 v190, v32, v36, -v188
	v_fma_f32 v191, v33, v36, v189
	v_add_f32_e32 v36, v190, v112
	v_add_f32_e32 v37, v191, v128
	v_mul_f32_e32 v188, v34, v37
	v_mul_f32_e32 v189, v35, v37
	v_fma_f32 v190, v32, v36, -v188
	v_fma_f32 v191, v33, v36, v189
	v_add_f32_e32 v36, v190, v113
	v_add_f32_e32 v37, v191, v129
	v_mul_f32_e32 v188, v34, v37
	v_mul_f32_e32 v189, v35, v37
	v_fma_f32 v190, v32, v36, -v188
	v_fma_f32 v191, v33, v36, v189
	v_add_f32_e32 v36, v190, v114
	v_add_f32_e32 v37, v191, v130
	v_mul_f32_e32 v188, v34, v37
	v_mul_f32_e32 v189, v35, v37
	v_fma_f32 v190, v32, v36, -v188
	v_fma_f32 v191, v33, v36, v189
	v_add_f32_e32 v36, v190, v115
	v_add_f32_e32 v37, v191, v131
	v_mul_f32_e32 v188, v34, v37
	v_mul_f32_e32 v189, v35, v37
	v_fma_f32 v190, v32, v36, -v188
	v_fma_f32 v191, v33, v36, v189
	v_add_f32_e32 v36, v190, v150
	v_add_f32_e32 v37, v191, v166
	v_mul_f32_e32 v188, v34, v37
	v_mul_f32_e32 v189, v35, v37
	v_fma_f32 v190, v32, v36, -v188
	v_fma_f32 v191, v33, v36, v189
	v_add_f32_e32 v36, v190, v151
	v_add_f32_e32 v37, v191, v167
	v_mul_f32_e32 v188, v34, v37
	v_mul_f32_e32 v189, v35, v37
	v_fma_f32 v190, v32, v36, -v188
	v_fma_f32 v191, v33, v36, v189
	v_add_f32_e32 v36, v190, v152
	v_add_f32_e32 v37, v191, v168
	v_mul_f32_e32 v188, v34, v37
	v_mul_f32_e32 v189, v35, v37
	v_fma_f32 v190, v32, v36, -v188
	v_fma_f32 v191, v33, v36, v189
	v_add_f32_e32 v36, v190, v153
	v_add_f32_e32 v37, v191, v169
	v_mul_f32_e32 v188, v34, v37
	v_mul_f32_e32 v189, v35, v37
	v_fma_f32 v190, v32, v36, -v188
	v_fma_f32 v191, v33, v36, v189
	v_add_f32_e32 v36, v190, v116
	v_add_f32_e32 v37, v191, v132
	v_mul_f32_e32 v188, v34, v37
	v_mul_f32_e32 v189, v35, v37
	v_fma_f32 v190, v32, v36, -v188
	v_fma_f32 v191, v33, v36, v189
	v_add_f32_e32 v36, v190, v117
	v_add_f32_e32 v37, v191, v133
	v_mul_f32_e32 v188, v34, v37
	v_mul_f32_e32 v189, v35, v37
	v_fma_f32 v190, v32, v36, -v188
	v_fma_f32 v191, v33, v36, v189
	v_add_f32_e32 v36, v190, v118
	v_add_f32_e32 v37, v191, v134
	v_mul_f32_e32 v188, v34, v37
	v_mul_f32_e32 v189, v35, v37
	v_fma_f32 v190, v32, v36, -v188
	v_fma_f32 v191, v33, v36, v189
	v_add_f32_e32 v36, v190, v119
	v_add_f32_e32 v37, v191, v135
	v_mul_f32_e32 v188, v34, v37
	v_mul_f32_e32 v189, v35, v37
	v_fma_f32 v190, v32, v36, -v188
	v_fma_f32 v191, v33, v36, v189
	v_add_f32_e32 v36, v190, v154
	v_add_f32_e32 v37, v191, v170
	v_mul_f32_e32 v188, v34, v37
	v_mul_f32_e32 v189, v35, v37
	v_fma_f32 v190, v32, v36, -v188
	v_fma_f32 v191, v33, v36, v189
	v_add_f32_e32 v36, v190, v155
	v_add_f32_e32 v37, v191, v171
	v_mul_f32_e32 v188, v34, v37
	v_mul_f32_e32 v189, v35, v37
	v_fma_f32 v190, v32, v36, -v188
	v_fma_f32 v191, v33, v36, v189
	v_add_f32_e32 v36, v190, v156
	v_add_f32_e32 v37, v191, v172
	v_mul_f32_e32 v188, v34, v37
	v_mul_f32_e32 v189, v35, v37
	v_fma_f32 v190, v32, v36, -v188
	v_fma_f32 v191, v33, v36, v189
	v_add_f32_e32 v36, v190, v157
	v_add_f32_e32 v37, v191, v173
	v_mul_f32_e32 v188, v34, v37
	v_mul_f32_e32 v189, v35, v37
	v_fma_f32 v190, v32, v36, -v188
	v_fma_f32 v191, v33, v36, v189
	v_add_f32_e32 v36, v190, v120
	v_add_f32_e32 v37, v191, v136
	v_mul_f32_e32 v188, v34, v37
	v_mul_f32_e32 v189, v35, v37
	v_fma_f32 v190, v32, v36, -v188
	v_fma_f32 v191, v33, v36, v189
	v_add_f32_e32 v36, v190, v121
	v_add_f32_e32 v37, v191, v137
	v_mul_f32_e32 v188, v34, v37
	v_mul_f32_e32 v189, v35, v37
	v_fma_f32 v190, v32, v36, -v188
	v_fma_f32 v191, v33, v36, v189
	v_add_f32_e32 v36, v190, v122
	v_add_f32_e32 v37, v191, v138
	v_mul_f32_e32 v188, v34, v37
	v_mul_f32_e32 v189, v35, v37
	v_fma_f32 v190, v32, v36, -v188
	v_fma_f32 v191, v33, v36, v189
	v_add_f32_e32 v36, v190, v123
	v_add_f32_e32 v37, v191, v139
	v_mul_f32_e32 v188, v34, v37
	v_mul_f32_e32 v189, v35, v37
	v_fma_f32 v190, v32, v36, -v188
	v_fma_f32 v191, v33, v36, v189
	v_add_f32_e32 v36, v190, v158
	v_add_f32_e32 v37, v191, v174
	v_mul_f32_e32 v188, v34, v37
	v_mul_f32_e32 v189, v35, v37
	v_fma_f32 v190, v32, v36, -v188
	v_fma_f32 v191, v33, v36, v189
	v_add_f32_e32 v36, v190, v159
	v_add_f32_e32 v37, v191, v175
	v_mul_f32_e32 v188, v34, v37
	v_mul_f32_e32 v189, v35, v37
	v_fma_f32 v190, v32, v36, -v188
	v_fma_f32 v191, v33, v36, v189
	v_add_f32_e32 v36, v190, v160
	v_add_f32_e32 v37, v191, v176
	v_mul_f32_e32 v188, v34, v37
	v_mul_f32_e32 v189, v35, v37
	v_fma_f32 v190, v32, v36, -v188
	v_fma_f32 v191, v33, v36, v189
	v_add_f32_e32 v36, v190, v161
	v_add_f32_e32 v37, v191, v177
	v_mov_b32_e32 v38, v37
	s_lshl_b32 s1, s1, 12
	s_lshl_b32 s0, s0, 5
	s_or_b32 s0, s0, s1
	v_or_b32_e32 v0, s0, v40
	v_lshlrev_b32_e32 v1, 1, v39
	v_readlane_b32 s0, v253, 38
	v_lshl_or_b32 v144, v0, 7, v1
	v_readlane_b32 s1, v253, 39
	v_readlane_b32 s2, v253, 40
	v_readlane_b32 s3, v253, 41
	v_lshl_add_u64 v[0:1], v[144:145], 2, s[0:1]
	v_readlane_b32 s4, v253, 42
	v_readlane_b32 s5, v253, 43
	v_readlane_b32 s6, v253, 44
	v_readlane_b32 s7, v253, 45
	global_store_dwordx2 v[0:1], v[36:37], off

; __device__ __forceinline__ bf f2bf(float f) { return (bf)(pk2(f, 0.f) & 0xFFFFu); }
; __device__ __forceinline__ void s5_pass2(const Params& p, int layer, int task, char* sm) {
;     ...
;       for (int l = 0; l < 32; l++) {
;         S5_STEP(sU + l * 16)
;         sS[l * 136 + lane] = f2bf(sr); sS[l * 136 + 64 + lane] = f2bf(si);
;       }
.LBB0_1796:
	v_add_u32_e32 v103, v79, v40
	v_and_b32_e32 v43, 31, v202
	v_lshrrev_b32_e32 v42, 5, v202
	v_lshlrev_b32_e32 v43, 6, v43
	v_lshl_add_u32 v43, v42, 2, v43
	v_add_u32_e32 v43, v79, v43
	ds_read2_b32 v[170:171], v43 offset0:0 offset1:2
	ds_read2_b32 v[172:173], v43 offset0:4 offset1:6
	ds_read2_b32 v[174:175], v43 offset0:8 offset1:10
	ds_read2_b32 v[176:177], v43 offset0:12 offset1:14
	s_waitcnt lgkmcnt(0)
	v_mfma_f32_32x32x2_f32 v[104:119], v170, v52, 0
	v_mfma_f32_32x32x2_f32 v[120:135], v170, v53, 0
	v_mfma_f32_32x32x2_f32 v[152:167], v170, v20, 0
	v_mfma_f32_32x32x2_f32 v[136:151], v170, v21, 0
	v_mfma_f32_32x32x2_f32 v[104:119], v171, v54, v[104:119]
	v_mfma_f32_32x32x2_f32 v[120:135], v171, v55, v[120:135]
	v_mfma_f32_32x32x2_f32 v[152:167], v171, v22, v[152:167]
	v_mfma_f32_32x32x2_f32 v[136:151], v171, v23, v[136:151]
	v_mfma_f32_32x32x2_f32 v[104:119], v172, v56, v[104:119]
	v_mfma_f32_32x32x2_f32 v[120:135], v172, v57, v[120:135]
	v_mfma_f32_32x32x2_f32 v[152:167], v172, v16, v[152:167]
	v_mfma_f32_32x32x2_f32 v[136:151], v172, v17, v[136:151]
	v_mfma_f32_32x32x2_f32 v[104:119], v173, v58, v[104:119]
	v_mfma_f32_32x32x2_f32 v[120:135], v173, v59, v[120:135]
	v_mfma_f32_32x32x2_f32 v[152:167], v173, v18, v[152:167]
	v_mfma_f32_32x32x2_f32 v[136:151], v173, v19, v[136:151]
	v_mfma_f32_32x32x2_f32 v[104:119], v174, v60, v[104:119]
	v_mfma_f32_32x32x2_f32 v[120:135], v174, v61, v[120:135]
	v_mfma_f32_32x32x2_f32 v[152:167], v174, v12, v[152:167]
	v_mfma_f32_32x32x2_f32 v[136:151], v174, v13, v[136:151]
	v_mfma_f32_32x32x2_f32 v[104:119], v175, v62, v[104:119]
	v_mfma_f32_32x32x2_f32 v[120:135], v175, v63, v[120:135]
	v_mfma_f32_32x32x2_f32 v[152:167], v175, v14, v[152:167]
	v_mfma_f32_32x32x2_f32 v[136:151], v175, v15, v[136:151]
	v_mfma_f32_32x32x2_f32 v[104:119], v176, v64, v[104:119]
	v_mfma_f32_32x32x2_f32 v[120:135], v176, v65, v[120:135]
	v_mfma_f32_32x32x2_f32 v[152:167], v176, v8, v[152:167]
	v_mfma_f32_32x32x2_f32 v[136:151], v176, v9, v[136:151]
	v_mfma_f32_32x32x2_f32 v[104:119], v177, v66, v[104:119]
	v_mfma_f32_32x32x2_f32 v[120:135], v177, v67, v[120:135]
	v_mfma_f32_32x32x2_f32 v[152:167], v177, v10, v[152:167]
	v_mfma_f32_32x32x2_f32 v[136:151], v177, v11, v[136:151]
	s_nop 7
	s_nop 7
	s_nop 7
	v_permlane32_swap_b32_e32 v104, v152
	v_permlane32_swap_b32_e32 v120, v136
	v_permlane32_swap_b32_e32 v105, v153
	v_permlane32_swap_b32_e32 v121, v137
	v_permlane32_swap_b32_e32 v106, v154
	v_permlane32_swap_b32_e32 v122, v138
	v_permlane32_swap_b32_e32 v107, v155
	v_permlane32_swap_b32_e32 v123, v139
	v_permlane32_swap_b32_e32 v108, v156
	v_permlane32_swap_b32_e32 v124, v140
	v_permlane32_swap_b32_e32 v109, v157
	v_permlane32_swap_b32_e32 v125, v141
	v_permlane32_swap_b32_e32 v110, v158
	v_permlane32_swap_b32_e32 v126, v142
	v_permlane32_swap_b32_e32 v111, v159
	v_permlane32_swap_b32_e32 v127, v143
	v_permlane32_swap_b32_e32 v112, v160
	v_permlane32_swap_b32_e32 v128, v144
	v_permlane32_swap_b32_e32 v113, v161
	v_permlane32_swap_b32_e32 v129, v145
	v_permlane32_swap_b32_e32 v114, v162
	v_permlane32_swap_b32_e32 v130, v146
	v_permlane32_swap_b32_e32 v115, v163
	v_permlane32_swap_b32_e32 v131, v147
	v_permlane32_swap_b32_e32 v116, v164
	v_permlane32_swap_b32_e32 v132, v148
	v_permlane32_swap_b32_e32 v117, v165
	v_permlane32_swap_b32_e32 v133, v149
	v_permlane32_swap_b32_e32 v118, v166
	v_permlane32_swap_b32_e32 v134, v150
	v_permlane32_swap_b32_e32 v119, v167
	v_permlane32_swap_b32_e32 v135, v151
	s_waitcnt vmcnt(5)
	v_mul_f32_e32 v76, v74, v71
	v_mul_f32_e32 v77, v75, v71
	v_fma_f32 v40, v68, v70, -v76
	v_fma_f32 v41, v69, v70, v77
	v_add_f32_e32 v70, v40, v104
	v_add_f32_e32 v71, v41, v120
	v_mul_f32_e32 v76, v74, v71
	v_mul_f32_e32 v77, v75, v71
	v_cvt_pk_bf16_f32 v42, v70, v71
	v_fma_f32 v40, v68, v70, -v76
	v_fma_f32 v41, v69, v70, v77
	ds_write_b16 v103, v42
	v_add_f32_e32 v70, v40, v105
	v_add_f32_e32 v71, v41, v121
	ds_write_b16_d16_hi v103, v42 offset:128
	v_mul_f32_e32 v76, v74, v71
	v_mul_f32_e32 v77, v75, v71
	v_cvt_pk_bf16_f32 v42, v70, v71
	v_fma_f32 v40, v68, v70, -v76
	v_fma_f32 v41, v69, v70, v77
	ds_write_b16 v103, v42 offset:272
	v_add_f32_e32 v70, v40, v106
	v_add_f32_e32 v71, v41, v122
	ds_write_b16_d16_hi v103, v42 offset:400
	v_mul_f32_e32 v76, v74, v71
	v_mul_f32_e32 v77, v75, v71
	v_cvt_pk_bf16_f32 v42, v70, v71
	v_fma_f32 v40, v68, v70, -v76
	v_fma_f32 v41, v69, v70, v77
	ds_write_b16 v103, v42 offset:544
	v_add_f32_e32 v70, v40, v107
	v_add_f32_e32 v71, v41, v123
	ds_write_b16_d16_hi v103, v42 offset:672
	v_mul_f32_e32 v76, v74, v71
	v_mul_f32_e32 v77, v75, v71
	v_cvt_pk_bf16_f32 v42, v70, v71
	v_fma_f32 v40, v68, v70, -v76
	v_fma_f32 v41, v69, v70, v77
	ds_write_b16 v103, v42 offset:816
	v_add_f32_e32 v70, v40, v152
	v_add_f32_e32 v71, v41, v136
	ds_write_b16_d16_hi v103, v42 offset:944
	v_mul_f32_e32 v76, v74, v71
	v_mul_f32_e32 v77, v75, v71
	v_cvt_pk_bf16_f32 v42, v70, v71
	v_fma_f32 v40, v68, v70, -v76
	v_fma_f32 v41, v69, v70, v77
	ds_write_b16 v103, v42 offset:1088
	v_add_f32_e32 v70, v40, v153
	v_add_f32_e32 v71, v41, v137
	ds_write_b16_d16_hi v103, v42 offset:1216
	v_mul_f32_e32 v76, v74, v71
	v_mul_f32_e32 v77, v75, v71
	v_cvt_pk_bf16_f32 v42, v70, v71
	v_fma_f32 v40, v68, v70, -v76
	v_fma_f32 v41, v69, v70, v77
	ds_write_b16 v103, v42 offset:1360
	v_add_f32_e32 v70, v40, v154
	v_add_f32_e32 v71, v41, v138
	ds_write_b16_d16_hi v103, v42 offset:1488
	v_mul_f32_e32 v76, v74, v71
	v_mul_f32_e32 v77, v75, v71
	v_cvt_pk_bf16_f32 v42, v70, v71
	v_fma_f32 v40, v68, v70, -v76
	v_fma_f32 v41, v69, v70, v77
	ds_write_b16 v103, v42 offset:1632
	v_add_f32_e32 v70, v40, v155
; __device__ __forceinline__ bf f2bf(float f) { return (bf)(pk2(f, 0.f) & 0xFFFFu); }
; __device__ __forceinline__ void s5_pass2(const Params& p, int layer, int task, char* sm) {
;     ...
;       for (int l = 0; l < 32; l++) {
;         S5_STEP(sU + l * 16)
;         sS[l * 136 + lane] = f2bf(sr); sS[l * 136 + 64 + lane] = f2bf(si);
;       }
	v_add_f32_e32 v71, v41, v139
	ds_write_b16_d16_hi v103, v42 offset:1760
	v_mul_f32_e32 v76, v74, v71
	v_mul_f32_e32 v77, v75, v71
	v_cvt_pk_bf16_f32 v42, v70, v71
	v_fma_f32 v40, v68, v70, -v76
	v_fma_f32 v41, v69, v70, v77
	ds_write_b16 v103, v42 offset:1904
	v_add_f32_e32 v70, v40, v108
	v_add_f32_e32 v71, v41, v124
	ds_write_b16_d16_hi v103, v42 offset:2032
	v_mul_f32_e32 v76, v74, v71
	v_mul_f32_e32 v77, v75, v71
	v_cvt_pk_bf16_f32 v42, v70, v71
	v_fma_f32 v40, v68, v70, -v76
	v_fma_f32 v41, v69, v70, v77
	ds_write_b16 v103, v42 offset:2176
	v_add_f32_e32 v70, v40, v109
	v_add_f32_e32 v71, v41, v125
	ds_write_b16_d16_hi v103, v42 offset:2304
	v_mul_f32_e32 v76, v74, v71
	v_mul_f32_e32 v77, v75, v71
	v_cvt_pk_bf16_f32 v42, v70, v71
	v_fma_f32 v40, v68, v70, -v76
	v_fma_f32 v41, v69, v70, v77
	ds_write_b16 v103, v42 offset:2448
	v_add_f32_e32 v70, v40, v110
	v_add_f32_e32 v71, v41, v126
	ds_write_b16_d16_hi v103, v42 offset:2576
	v_mul_f32_e32 v76, v74, v71
	v_mul_f32_e32 v77, v75, v71
	v_cvt_pk_bf16_f32 v42, v70, v71
	v_fma_f32 v40, v68, v70, -v76
	v_fma_f32 v41, v69, v70, v77
	ds_write_b16 v103, v42 offset:2720
	v_add_f32_e32 v70, v40, v111
	v_add_f32_e32 v71, v41, v127
	ds_write_b16_d16_hi v103, v42 offset:2848
	v_mul_f32_e32 v76, v74, v71
	v_mul_f32_e32 v77, v75, v71
	v_cvt_pk_bf16_f32 v42, v70, v71
	v_fma_f32 v40, v68, v70, -v76
	v_fma_f32 v41, v69, v70, v77
	ds_write_b16 v103, v42 offset:2992
	v_add_f32_e32 v70, v40, v156
	v_add_f32_e32 v71, v41, v140
	ds_write_b16_d16_hi v103, v42 offset:3120
	v_mul_f32_e32 v76, v74, v71
	v_mul_f32_e32 v77, v75, v71
	v_cvt_pk_bf16_f32 v42, v70, v71
	v_fma_f32 v40, v68, v70, -v76
	v_fma_f32 v41, v69, v70, v77
	ds_write_b16 v103, v42 offset:3264
	v_add_f32_e32 v70, v40, v157
	v_add_f32_e32 v71, v41, v141
	ds_write_b16_d16_hi v103, v42 offset:3392
	v_mul_f32_e32 v76, v74, v71
	v_mul_f32_e32 v77, v75, v71
	v_cvt_pk_bf16_f32 v42, v70, v71
	v_fma_f32 v40, v68, v70, -v76
	v_fma_f32 v41, v69, v70, v77
	ds_write_b16 v103, v42 offset:3536
	v_add_f32_e32 v70, v40, v158
	v_add_f32_e32 v71, v41, v142
	ds_write_b16_d16_hi v103, v42 offset:3664
	v_mul_f32_e32 v76, v74, v71
	v_mul_f32_e32 v77, v75, v71
	v_cvt_pk_bf16_f32 v42, v70, v71
	v_fma_f32 v40, v68, v70, -v76
	v_fma_f32 v41, v69, v70, v77
	ds_write_b16 v103, v42 offset:3808
	v_add_f32_e32 v70, v40, v159
	v_add_f32_e32 v71, v41, v143
	ds_write_b16_d16_hi v103, v42 offset:3936
	v_mul_f32_e32 v76, v74, v71
	v_mul_f32_e32 v77, v75, v71
	v_cvt_pk_bf16_f32 v42, v70, v71
	v_fma_f32 v40, v68, v70, -v76
	v_fma_f32 v41, v69, v70, v77
	ds_write_b16 v103, v42 offset:4080
	v_add_f32_e32 v70, v40, v112
	v_add_f32_e32 v71, v41, v128
	ds_write_b16_d16_hi v103, v42 offset:4208
	v_mul_f32_e32 v76, v74, v71
	v_mul_f32_e32 v77, v75, v71
	v_cvt_pk_bf16_f32 v42, v70, v71
	v_fma_f32 v40, v68, v70, -v76
	v_fma_f32 v41, v69, v70, v77
	ds_write_b16 v103, v42 offset:4352
	v_add_f32_e32 v70, v40, v113
	v_add_f32_e32 v71, v41, v129
	ds_write_b16_d16_hi v103, v42 offset:4480
	v_mul_f32_e32 v76, v74, v71
	v_mul_f32_e32 v77, v75, v71
	v_cvt_pk_bf16_f32 v42, v70, v71
	v_fma_f32 v40, v68, v70, -v76
	v_fma_f32 v41, v69, v70, v77
	ds_write_b16 v103, v42 offset:4624
	v_add_f32_e32 v70, v40, v114
	v_add_f32_e32 v71, v41, v130
	ds_write_b16_d16_hi v103, v42 offset:4752
	v_mul_f32_e32 v76, v74, v71
	v_mul_f32_e32 v77, v75, v71
	v_cvt_pk_bf16_f32 v42, v70, v71
	v_fma_f32 v40, v68, v70, -v76
	v_fma_f32 v41, v69, v70, v77
	ds_write_b16 v103, v42 offset:4896
	v_add_f32_e32 v70, v40, v115
	v_add_f32_e32 v71, v41, v131
	ds_write_b16_d16_hi v103, v42 offset:5024
	v_mul_f32_e32 v76, v74, v71
	v_mul_f32_e32 v77, v75, v71
	v_cvt_pk_bf16_f32 v42, v70, v71
	v_fma_f32 v40, v68, v70, -v76
	v_fma_f32 v41, v69, v70, v77
	ds_write_b16 v103, v42 offset:5168
	v_add_f32_e32 v70, v40, v160
	v_add_f32_e32 v71, v41, v144
	ds_write_b16_d16_hi v103, v42 offset:5296
	v_mul_f32_e32 v76, v74, v71
	v_mul_f32_e32 v77, v75, v71
	v_cvt_pk_bf16_f32 v42, v70, v71
	v_fma_f32 v40, v68, v70, -v76
	v_fma_f32 v41, v69, v70, v77
	ds_write_b16 v103, v42 offset:5440
	v_add_f32_e32 v70, v40, v161
	v_add_f32_e32 v71, v41, v145
	ds_write_b16_d16_hi v103, v42 offset:5568
	v_mul_f32_e32 v76, v74, v71
	v_mul_f32_e32 v77, v75, v71
	v_cvt_pk_bf16_f32 v42, v70, v71
	v_fma_f32 v40, v68, v70, -v76
	v_fma_f32 v41, v69, v70, v77
	ds_write_b16 v103, v42 offset:5712
	v_add_f32_e32 v70, v40, v162
	v_add_f32_e32 v71, v41, v146
	ds_write_b16_d16_hi v103, v42 offset:5840
	v_mul_f32_e32 v76, v74, v71
	v_mul_f32_e32 v77, v75, v71
	v_cvt_pk_bf16_f32 v42, v70, v71
	v_fma_f32 v40, v68, v70, -v76
	v_fma_f32 v41, v69, v70, v77
	ds_write_b16 v103, v42 offset:5984
	v_add_f32_e32 v70, v40, v163
	v_add_f32_e32 v71, v41, v147
	ds_write_b16_d16_hi v103, v42 offset:6112
	v_mul_f32_e32 v76, v74, v71
	v_mul_f32_e32 v77, v75, v71
	v_cvt_pk_bf16_f32 v42, v70, v71
	v_fma_f32 v40, v68, v70, -v76
	v_fma_f32 v41, v69, v70, v77
	ds_write_b16 v103, v42 offset:6256
	v_add_f32_e32 v70, v40, v116
	v_add_f32_e32 v71, v41, v132
	ds_write_b16_d16_hi v103, v42 offset:6384
	v_mul_f32_e32 v76, v74, v71
	v_mul_f32_e32 v77, v75, v71
	v_cvt_pk_bf16_f32 v42, v70, v71
	v_fma_f32 v40, v68, v70, -v76
	v_fma_f32 v41, v69, v70, v77
	ds_write_b16 v103, v42 offset:6528
	v_add_f32_e32 v70, v40, v117
	v_add_f32_e32 v71, v41, v133
	ds_write_b16_d16_hi v103, v42 offset:6656
	v_mul_f32_e32 v76, v74, v71
	v_mul_f32_e32 v77, v75, v71
	v_cvt_pk_bf16_f32 v42, v70, v71
	v_fma_f32 v40, v68, v70, -v76
	v_fma_f32 v41, v69, v70, v77
	ds_write_b16 v103, v42 offset:6800
	v_add_f32_e32 v70, v40, v118
	v_add_f32_e32 v71, v41, v134
	ds_write_b16_d16_hi v103, v42 offset:6928
	v_mul_f32_e32 v76, v74, v71
; __device__ __forceinline__ float ozero() { float z = 0.f; asm volatile("" : "+v"(z)); return z; }
; __device__ __forceinline__ bf f2bf(float f) { return (bf)(pk2(f, 0.f) & 0xFFFFu); }
; __device__ __forceinline__ f32x4 mfma16(bf16x8 a, bf16x8 b, f32x4 c) { return __builtin_amdgcn_mfma_f32_16x16x32_bf16(a, b, c, 0, 0, 0); }
; __device__ __forceinline__ float geluf_(float x) {
;   float u = 0.7978845608028654f * (x + 0.044715f * x * x * x);
;   float t = 1.f - 2.f * __builtin_amdgcn_rcpf(1.f + __expf(2.f * u));
;   return 0.5f * x * (1.f + t);
; }
; __device__ __forceinline__ void s5_pass2(const Params& p, int layer, int task, char* sm) {
;     ...
;       for (int l = 0; l < 32; l++) {
;         S5_STEP(sU + l * 16)
;         sS[l * 136 + lane] = f2bf(sr); sS[l * 136 + 64 + lane] = f2bf(si);
;       }
;       __builtin_amdgcn_wave_barrier();
; #pragma unroll
;       for (int mb = 0; mb < 2; mb++) {
;         const float z_ = ozero(); f32x4 acc = {z_, z_, z_, z_};
; #pragma unroll
;         for (int ks = 0; ks < 4; ks++) {
;           bf16x8 af = *(const bf16x8*)(sS + (16 * mb + (lane & 15)) * 136 + ks * 32 + 8 * (lane >> 4));
;           acc = mfma16(af, cf[ks], acc);
;         }
; #pragma unroll
;         for (int r = 0; r < 4; r++) {
;           const int l = 16 * mb + 4 * (lane >> 4) + r;
;           float y = acc[r] + dsk * sU[l * 16 + (lane & 15)];
;           p.YG[(tok0 + sub * 32 + l) * 512 + g * 16 + (lane & 15)] = f2bf(geluf_(y));
;         }
;       }
	v_mul_f32_e32 v77, v75, v71
	v_cvt_pk_bf16_f32 v42, v70, v71
	v_fma_f32 v40, v68, v70, -v76
	v_fma_f32 v41, v69, v70, v77
	ds_write_b16 v103, v42 offset:7072
	v_add_f32_e32 v70, v40, v119
	v_add_f32_e32 v71, v41, v135
	ds_write_b16_d16_hi v103, v42 offset:7200
	v_mul_f32_e32 v76, v74, v71
	v_mul_f32_e32 v77, v75, v71
	v_cvt_pk_bf16_f32 v42, v70, v71
	v_fma_f32 v40, v68, v70, -v76
	v_fma_f32 v41, v69, v70, v77
	ds_write_b16 v103, v42 offset:7344
	v_add_f32_e32 v70, v40, v164
	v_add_f32_e32 v71, v41, v148
	ds_write_b16_d16_hi v103, v42 offset:7472
	v_mul_f32_e32 v76, v74, v71
	v_mul_f32_e32 v77, v75, v71
	v_cvt_pk_bf16_f32 v42, v70, v71
	v_fma_f32 v40, v68, v70, -v76
	v_fma_f32 v41, v69, v70, v77
	ds_write_b16 v103, v42 offset:7616
	v_add_f32_e32 v70, v40, v165
	v_add_f32_e32 v71, v41, v149
	ds_write_b16_d16_hi v103, v42 offset:7744
	v_mul_f32_e32 v76, v74, v71
	v_mul_f32_e32 v77, v75, v71
	v_cvt_pk_bf16_f32 v42, v70, v71
	v_fma_f32 v40, v68, v70, -v76
	v_fma_f32 v41, v69, v70, v77
	ds_write_b16 v103, v42 offset:7888
	v_add_f32_e32 v70, v40, v166
	v_add_f32_e32 v71, v41, v150
	ds_write_b16_d16_hi v103, v42 offset:8016
	v_mul_f32_e32 v76, v74, v71
	v_mul_f32_e32 v77, v75, v71
	v_cvt_pk_bf16_f32 v42, v70, v71
	v_fma_f32 v40, v68, v70, -v76
	v_fma_f32 v41, v69, v70, v77
	ds_write_b16 v103, v42 offset:8160
	v_add_f32_e32 v70, v40, v167
	v_add_f32_e32 v71, v41, v151
	ds_write_b16_d16_hi v103, v42 offset:8288
	v_cvt_pk_bf16_f32 v42, v70, v71
	ds_write_b16 v103, v42 offset:8432
	ds_write_b16_d16_hi v103, v42 offset:8560
	s_waitcnt lgkmcnt(0)
	v_mov_b32_e32 v145, 0
	v_mov_b32_e32 v40, v145
	ds_read_b128 v[104:107], v100 offset:2048
	ds_read_b32 v76, v83
	v_mov_b32_e32 v41, v40
	v_mov_b32_e32 v42, v40
	v_mov_b32_e32 v43, v40
	s_lshl_b32 s9, s11, 5
	v_mov_b32_e32 v77, s5
	s_cmp_eq_u32 s8, 4
	s_waitcnt vmcnt(4) lgkmcnt(1)
	v_mfma_f32_16x16x32_bf16 v[40:43], v[104:107], v[24:27], v[40:43]
	ds_read_b128 v[104:107], v100 offset:2112
	s_waitcnt vmcnt(3) lgkmcnt(0)
	v_mfma_f32_16x16x32_bf16 v[40:43], v[104:107], v[28:31], v[40:43]
	ds_read_b128 v[104:107], v100 offset:2176
	s_waitcnt vmcnt(2) lgkmcnt(0)
	v_mfma_f32_16x16x32_bf16 v[40:43], v[104:107], v[32:35], v[40:43]
	ds_read_b128 v[104:107], v100 offset:2240
	s_waitcnt vmcnt(1) lgkmcnt(0)
	v_mfma_f32_16x16x32_bf16 v[40:43], v[104:107], v[36:39], v[40:43]
	s_waitcnt vmcnt(0)
	s_nop 6
	v_fma_f32 v40, v102, v76, v40
	v_mul_f32_e32 v76, 0x3d372713, v40
	v_mul_f32_e32 v76, v40, v76
	v_fma_f32 v76, v40, v76, v40
	v_mul_f32_e32 v76, 0x3f4c422a, v76
	v_add_f32_e32 v76, v76, v76
	v_mul_f32_e32 v76, 0x3fb8aa3b, v76
	v_exp_f32_e32 v76, v76
	v_mul_f32_e32 v40, 0.5, v40
	v_add_f32_e32 v76, 1.0, v76
	v_rcp_f32_e32 v76, v76
	s_nop 0
	v_fma_f32 v76, v76, -2.0, 1.0
	v_add_f32_e32 v76, 1.0, v76
	v_mul_f32_e32 v40, v40, v76
	v_or_b32_e32 v76, s9, v82
	v_or_b32_e32 v76, s4, v76
	v_lshlrev_b64 v[104:105], 10, v[76:77]
	v_cvt_pk_bf16_f32 v40, v40, s0
	v_lshl_add_u64 v[104:105], v[72:73], 0, v[104:105]
	global_store_short v[104:105], v40, off
	ds_read_b32 v40, v85
	s_waitcnt lgkmcnt(0)
	v_fma_f32 v40, v102, v40, v41
	v_mul_f32_e32 v41, 0x3d372713, v40
	v_mul_f32_e32 v41, v40, v41
	v_fma_f32 v41, v40, v41, v40
	v_mul_f32_e32 v41, 0x3f4c422a, v41
	v_add_f32_e32 v41, v41, v41
	v_mul_f32_e32 v41, 0x3fb8aa3b, v41
	v_exp_f32_e32 v41, v41
	v_mul_f32_e32 v40, 0.5, v40
	v_add_f32_e32 v41, 1.0, v41
	v_rcp_f32_e32 v41, v41
	s_nop 0
	v_fma_f32 v41, v41, -2.0, 1.0
	v_add_f32_e32 v41, 1.0, v41
	v_mul_f32_e32 v40, v40, v41
	v_cvt_pk_bf16_f32 v103, v40, s0
	v_or_b32_e32 v40, s9, v84
	v_or_b32_e32 v76, s4, v40
	v_lshlrev_b64 v[40:41], 10, v[76:77]
	v_lshl_add_u64 v[40:41], v[72:73], 0, v[40:41]
	global_store_short v[40:41], v103, off
	ds_read_b32 v40, v87
	s_waitcnt lgkmcnt(0)
	v_fma_f32 v40, v102, v40, v42
	v_mul_f32_e32 v41, 0x3d372713, v40
	v_mul_f32_e32 v41, v40, v41
	v_fma_f32 v41, v40, v41, v40
	v_mul_f32_e32 v41, 0x3f4c422a, v41
	v_add_f32_e32 v41, v41, v41
	v_mul_f32_e32 v41, 0x3fb8aa3b, v41
	v_exp_f32_e32 v41, v41
	v_mul_f32_e32 v40, 0.5, v40
	v_add_f32_e32 v41, 1.0, v41
	v_rcp_f32_e32 v41, v41
	s_nop 0
	v_fma_f32 v41, v41, -2.0, 1.0
	v_add_f32_e32 v41, 1.0, v41
	v_mul_f32_e32 v40, v40, v41
	v_cvt_pk_bf16_f32 v42, v40, s0
	v_or_b32_e32 v40, s9, v86
	v_or_b32_e32 v76, s4, v40
	v_lshlrev_b64 v[40:41], 10, v[76:77]
	v_lshl_add_u64 v[40:41], v[72:73], 0, v[40:41]
	global_store_short v[40:41], v42, off
	ds_read_b32 v40, v89
	s_waitcnt lgkmcnt(0)
; __device__ __forceinline__ float ozero() { float z = 0.f; asm volatile("" : "+v"(z)); return z; }
; __device__ __forceinline__ bf f2bf(float f) { return (bf)(pk2(f, 0.f) & 0xFFFFu); }
; __device__ __forceinline__ f32x4 mfma16(bf16x8 a, bf16x8 b, f32x4 c) { return __builtin_amdgcn_mfma_f32_16x16x32_bf16(a, b, c, 0, 0, 0); }
; __device__ __forceinline__ float geluf_(float x) {
;   float u = 0.7978845608028654f * (x + 0.044715f * x * x * x);
;   float t = 1.f - 2.f * __builtin_amdgcn_rcpf(1.f + __expf(2.f * u));
;   return 0.5f * x * (1.f + t);
; }
; __device__ __forceinline__ void s5_pass2(const Params& p, int layer, int task, char* sm) {
;     ...
; #pragma unroll
;       for (int mb = 0; mb < 2; mb++) {
;         const float z_ = ozero(); f32x4 acc = {z_, z_, z_, z_};
; #pragma unroll
;         for (int ks = 0; ks < 4; ks++) {
;           bf16x8 af = *(const bf16x8*)(sS + (16 * mb + (lane & 15)) * 136 + ks * 32 + 8 * (lane >> 4));
;           acc = mfma16(af, cf[ks], acc);
;         }
; #pragma unroll
;         for (int r = 0; r < 4; r++) {
;           const int l = 16 * mb + 4 * (lane >> 4) + r;
;           float y = acc[r] + dsk * sU[l * 16 + (lane & 15)];
;           p.YG[(tok0 + sub * 32 + l) * 512 + g * 16 + (lane & 15)] = f2bf(geluf_(y));
;         }
;       }
	v_fmac_f32_e32 v43, v102, v40
	v_mul_f32_e32 v40, 0x3d372713, v43
	v_mul_f32_e32 v40, v43, v40
	v_fma_f32 v40, v43, v40, v43
	v_mul_f32_e32 v40, 0x3f4c422a, v40
	v_add_f32_e32 v40, v40, v40
	v_mul_f32_e32 v40, 0x3fb8aa3b, v40
	v_exp_f32_e32 v40, v40
	v_mul_f32_e32 v41, 0.5, v43
	v_add_f32_e32 v40, 1.0, v40
	v_rcp_f32_e32 v40, v40
	s_nop 0
	v_fma_f32 v40, v40, -2.0, 1.0
	v_add_f32_e32 v40, 1.0, v40
	v_mul_f32_e32 v40, v41, v40
	v_cvt_pk_bf16_f32 v42, v40, s0
	v_or_b32_e32 v40, s9, v88
	v_or_b32_e32 v76, s4, v40
	v_lshlrev_b64 v[40:41], 10, v[76:77]
	v_lshl_add_u64 v[40:41], v[72:73], 0, v[40:41]
	global_store_short v[40:41], v42, off
	v_mov_b32_e32 v40, v145
	ds_read_b128 v[104:107], v100 offset:6400
	ds_read_b32 v76, v91
	v_mov_b32_e32 v41, v40
	v_mov_b32_e32 v42, v40
	v_mov_b32_e32 v43, v40
	s_waitcnt lgkmcnt(1)
	s_nop 0
	v_mfma_f32_16x16x32_bf16 v[40:43], v[104:107], v[24:27], v[40:43]
	ds_read_b128 v[104:107], v100 offset:6464
	s_waitcnt lgkmcnt(0)
	v_mfma_f32_16x16x32_bf16 v[40:43], v[104:107], v[28:31], v[40:43]
	ds_read_b128 v[104:107], v100 offset:6528
	s_waitcnt lgkmcnt(0)
	v_mfma_f32_16x16x32_bf16 v[40:43], v[104:107], v[32:35], v[40:43]
	ds_read_b128 v[104:107], v100 offset:6592
	s_waitcnt lgkmcnt(0)
	v_mfma_f32_16x16x32_bf16 v[40:43], v[104:107], v[36:39], v[40:43]
	s_nop 7
	v_fma_f32 v40, v102, v76, v40
	v_mul_f32_e32 v76, 0x3d372713, v40
	v_mul_f32_e32 v76, v40, v76
	v_fma_f32 v76, v40, v76, v40
	v_mul_f32_e32 v76, 0x3f4c422a, v76
	v_add_f32_e32 v76, v76, v76
	v_mul_f32_e32 v76, 0x3fb8aa3b, v76
	v_exp_f32_e32 v76, v76
	v_mul_f32_e32 v40, 0.5, v40
	v_add_f32_e32 v76, 1.0, v76
	v_rcp_f32_e32 v76, v76
	s_nop 0
	v_fma_f32 v76, v76, -2.0, 1.0
	v_add_f32_e32 v76, 1.0, v76
	v_mul_f32_e32 v40, v40, v76
	v_or_b32_e32 v76, s9, v90
	v_or_b32_e32 v76, s4, v76
	v_lshlrev_b64 v[104:105], 10, v[76:77]
	v_cvt_pk_bf16_f32 v40, v40, s0
	v_lshl_add_u64 v[104:105], v[72:73], 0, v[104:105]
	global_store_short v[104:105], v40, off
	ds_read_b32 v40, v93
	s_waitcnt lgkmcnt(0)
	v_fma_f32 v40, v102, v40, v41
	v_mul_f32_e32 v41, 0x3d372713, v40
	v_mul_f32_e32 v41, v40, v41
	v_fma_f32 v41, v40, v41, v40
	v_mul_f32_e32 v41, 0x3f4c422a, v41
	v_add_f32_e32 v41, v41, v41
	v_mul_f32_e32 v41, 0x3fb8aa3b, v41
	v_exp_f32_e32 v41, v41
	v_mul_f32_e32 v40, 0.5, v40
	v_add_f32_e32 v41, 1.0, v41
	v_rcp_f32_e32 v41, v41
	s_nop 0
	v_fma_f32 v41, v41, -2.0, 1.0
	v_add_f32_e32 v41, 1.0, v41
	v_mul_f32_e32 v40, v40, v41
	v_cvt_pk_bf16_f32 v103, v40, s0
	v_or_b32_e32 v40, s9, v92
	v_or_b32_e32 v76, s4, v40
	v_lshlrev_b64 v[40:41], 10, v[76:77]
	v_lshl_add_u64 v[40:41], v[72:73], 0, v[40:41]
	global_store_short v[40:41], v103, off
	ds_read_b32 v40, v95
	s_waitcnt lgkmcnt(0)
	v_fma_f32 v40, v102, v40, v42
	v_mul_f32_e32 v41, 0x3d372713, v40
	v_mul_f32_e32 v41, v40, v41
	v_fma_f32 v41, v40, v41, v40
	v_mul_f32_e32 v41, 0x3f4c422a, v41
	v_add_f32_e32 v41, v41, v41
	v_mul_f32_e32 v41, 0x3fb8aa3b, v41
	v_exp_f32_e32 v41, v41
	v_mul_f32_e32 v40, 0.5, v40
	v_add_f32_e32 v41, 1.0, v41
	v_rcp_f32_e32 v41, v41
	s_nop 0
	v_fma_f32 v41, v41, -2.0, 1.0
	v_add_f32_e32 v41, 1.0, v41
	v_mul_f32_e32 v40, v40, v41
	v_cvt_pk_bf16_f32 v42, v40, s0
	v_or_b32_e32 v40, s9, v94
	v_or_b32_e32 v76, s4, v40
	v_lshlrev_b64 v[40:41], 10, v[76:77]
	v_lshl_add_u64 v[40:41], v[72:73], 0, v[40:41]
	global_store_short v[40:41], v42, off
	ds_read_b32 v40, v97
	s_waitcnt lgkmcnt(0)
	v_fmac_f32_e32 v43, v102, v40
	v_mul_f32_e32 v40, 0x3d372713, v43
	v_mul_f32_e32 v40, v43, v40
	v_fma_f32 v40, v43, v40, v43
	v_mul_f32_e32 v40, 0x3f4c422a, v40
	v_add_f32_e32 v40, v40, v40
	v_mul_f32_e32 v40, 0x3fb8aa3b, v40
	v_exp_f32_e32 v40, v40
	v_mul_f32_e32 v41, 0.5, v43
	v_add_f32_e32 v40, 1.0, v40
	v_rcp_f32_e32 v40, v40
	s_nop 0
	v_fma_f32 v40, v40, -2.0, 1.0
	v_add_f32_e32 v40, 1.0, v40
	v_mul_f32_e32 v40, v41, v40
	v_cvt_pk_bf16_f32 v42, v40, s0
	v_or_b32_e32 v40, s9, v96
	v_or_b32_e32 v76, s4, v40
	v_lshlrev_b64 v[40:41], 10, v[76:77]
	v_lshl_add_u64 v[40:41], v[72:73], 0, v[40:41]
	global_store_short v[40:41], v42, off
	s_cbranch_scc1 .LBB0_1789
	s_mov_b32 s11, s8
	s_branch .LBB0_1791

; __device__ __forceinline__ bf f2bf(float f) { return (bf)(pk2(f, 0.f) & 0xFFFFu); }
; __device__ __forceinline__ void s5_pass2(const Params& p, int layer, int task, char* sm) {
;     ...
;       for (int l = 0; l < 32; l++) {
;         S5_STEP(sU + l * 16)
;         sS[l * 136 + lane] = f2bf(sr); sS[l * 136 + 64 + lane] = f2bf(si);
;       }
.LBB0_2060:
	v_add_u32_e32 v103, v79, v40
	v_and_b32_e32 v43, 31, v202
	v_lshrrev_b32_e32 v42, 5, v202
	v_lshlrev_b32_e32 v43, 6, v43
	v_lshl_add_u32 v43, v42, 2, v43
	v_add_u32_e32 v43, v79, v43
	ds_read2_b32 v[170:171], v43 offset0:0 offset1:2
	ds_read2_b32 v[172:173], v43 offset0:4 offset1:6
	ds_read2_b32 v[174:175], v43 offset0:8 offset1:10
	ds_read2_b32 v[176:177], v43 offset0:12 offset1:14
	s_waitcnt lgkmcnt(0)
	v_mfma_f32_32x32x2_f32 v[104:119], v170, v52, 0
	v_mfma_f32_32x32x2_f32 v[120:135], v170, v53, 0
	v_mfma_f32_32x32x2_f32 v[152:167], v170, v20, 0
	v_mfma_f32_32x32x2_f32 v[136:151], v170, v21, 0
	v_mfma_f32_32x32x2_f32 v[104:119], v171, v54, v[104:119]
	v_mfma_f32_32x32x2_f32 v[120:135], v171, v55, v[120:135]
	v_mfma_f32_32x32x2_f32 v[152:167], v171, v22, v[152:167]
	v_mfma_f32_32x32x2_f32 v[136:151], v171, v23, v[136:151]
	v_mfma_f32_32x32x2_f32 v[104:119], v172, v56, v[104:119]
	v_mfma_f32_32x32x2_f32 v[120:135], v172, v57, v[120:135]
	v_mfma_f32_32x32x2_f32 v[152:167], v172, v16, v[152:167]
	v_mfma_f32_32x32x2_f32 v[136:151], v172, v17, v[136:151]
	v_mfma_f32_32x32x2_f32 v[104:119], v173, v58, v[104:119]
	v_mfma_f32_32x32x2_f32 v[120:135], v173, v59, v[120:135]
	v_mfma_f32_32x32x2_f32 v[152:167], v173, v18, v[152:167]
	v_mfma_f32_32x32x2_f32 v[136:151], v173, v19, v[136:151]
	v_mfma_f32_32x32x2_f32 v[104:119], v174, v60, v[104:119]
	v_mfma_f32_32x32x2_f32 v[120:135], v174, v61, v[120:135]
	v_mfma_f32_32x32x2_f32 v[152:167], v174, v12, v[152:167]
	v_mfma_f32_32x32x2_f32 v[136:151], v174, v13, v[136:151]
	v_mfma_f32_32x32x2_f32 v[104:119], v175, v62, v[104:119]
	v_mfma_f32_32x32x2_f32 v[120:135], v175, v63, v[120:135]
	v_mfma_f32_32x32x2_f32 v[152:167], v175, v14, v[152:167]
	v_mfma_f32_32x32x2_f32 v[136:151], v175, v15, v[136:151]
	v_mfma_f32_32x32x2_f32 v[104:119], v176, v64, v[104:119]
	v_mfma_f32_32x32x2_f32 v[120:135], v176, v65, v[120:135]
	v_mfma_f32_32x32x2_f32 v[152:167], v176, v8, v[152:167]
	v_mfma_f32_32x32x2_f32 v[136:151], v176, v9, v[136:151]
	v_mfma_f32_32x32x2_f32 v[104:119], v177, v66, v[104:119]
	v_mfma_f32_32x32x2_f32 v[120:135], v177, v67, v[120:135]
	v_mfma_f32_32x32x2_f32 v[152:167], v177, v10, v[152:167]
	v_mfma_f32_32x32x2_f32 v[136:151], v177, v11, v[136:151]
	s_nop 7
	s_nop 7
	s_nop 7
	v_permlane32_swap_b32_e32 v104, v152
	v_permlane32_swap_b32_e32 v120, v136
	v_permlane32_swap_b32_e32 v105, v153
	v_permlane32_swap_b32_e32 v121, v137
	v_permlane32_swap_b32_e32 v106, v154
	v_permlane32_swap_b32_e32 v122, v138
	v_permlane32_swap_b32_e32 v107, v155
	v_permlane32_swap_b32_e32 v123, v139
	v_permlane32_swap_b32_e32 v108, v156
	v_permlane32_swap_b32_e32 v124, v140
	v_permlane32_swap_b32_e32 v109, v157
	v_permlane32_swap_b32_e32 v125, v141
	v_permlane32_swap_b32_e32 v110, v158
	v_permlane32_swap_b32_e32 v126, v142
	v_permlane32_swap_b32_e32 v111, v159
	v_permlane32_swap_b32_e32 v127, v143
	v_permlane32_swap_b32_e32 v112, v160
	v_permlane32_swap_b32_e32 v128, v144
	v_permlane32_swap_b32_e32 v113, v161
	v_permlane32_swap_b32_e32 v129, v145
	v_permlane32_swap_b32_e32 v114, v162
	v_permlane32_swap_b32_e32 v130, v146
	v_permlane32_swap_b32_e32 v115, v163
	v_permlane32_swap_b32_e32 v131, v147
	v_permlane32_swap_b32_e32 v116, v164
	v_permlane32_swap_b32_e32 v132, v148
	v_permlane32_swap_b32_e32 v117, v165
	v_permlane32_swap_b32_e32 v133, v149
	v_permlane32_swap_b32_e32 v118, v166
	v_permlane32_swap_b32_e32 v134, v150
	v_permlane32_swap_b32_e32 v119, v167
	v_permlane32_swap_b32_e32 v135, v151
	s_waitcnt vmcnt(5)
	v_mul_f32_e32 v76, v74, v71
	v_mul_f32_e32 v77, v75, v71
	v_fma_f32 v40, v68, v70, -v76
	v_fma_f32 v41, v69, v70, v77
	v_add_f32_e32 v70, v40, v104
	v_add_f32_e32 v71, v41, v120
	v_mul_f32_e32 v76, v74, v71
	v_mul_f32_e32 v77, v75, v71
	v_cvt_pk_bf16_f32 v42, v70, v71
	v_fma_f32 v40, v68, v70, -v76
	v_fma_f32 v41, v69, v70, v77
	ds_write_b16 v103, v42
	v_add_f32_e32 v70, v40, v105
	v_add_f32_e32 v71, v41, v121
	ds_write_b16_d16_hi v103, v42 offset:128
	v_mul_f32_e32 v76, v74, v71
	v_mul_f32_e32 v77, v75, v71
	v_cvt_pk_bf16_f32 v42, v70, v71
	v_fma_f32 v40, v68, v70, -v76
	v_fma_f32 v41, v69, v70, v77
	ds_write_b16 v103, v42 offset:272
	v_add_f32_e32 v70, v40, v106
	v_add_f32_e32 v71, v41, v122
	ds_write_b16_d16_hi v103, v42 offset:400
	v_mul_f32_e32 v76, v74, v71
	v_mul_f32_e32 v77, v75, v71
	v_cvt_pk_bf16_f32 v42, v70, v71
	v_fma_f32 v40, v68, v70, -v76
	v_fma_f32 v41, v69, v70, v77
	ds_write_b16 v103, v42 offset:544
	v_add_f32_e32 v70, v40, v107
	v_add_f32_e32 v71, v41, v123
	ds_write_b16_d16_hi v103, v42 offset:672
	v_mul_f32_e32 v76, v74, v71
	v_mul_f32_e32 v77, v75, v71
	v_cvt_pk_bf16_f32 v42, v70, v71
	v_fma_f32 v40, v68, v70, -v76
	v_fma_f32 v41, v69, v70, v77
	ds_write_b16 v103, v42 offset:816
	v_add_f32_e32 v70, v40, v152
	v_add_f32_e32 v71, v41, v136
	ds_write_b16_d16_hi v103, v42 offset:944
	v_mul_f32_e32 v76, v74, v71
	v_mul_f32_e32 v77, v75, v71
	v_cvt_pk_bf16_f32 v42, v70, v71
	v_fma_f32 v40, v68, v70, -v76
	v_fma_f32 v41, v69, v70, v77
	ds_write_b16 v103, v42 offset:1088
	v_add_f32_e32 v70, v40, v153
	v_add_f32_e32 v71, v41, v137
	ds_write_b16_d16_hi v103, v42 offset:1216
	v_mul_f32_e32 v76, v74, v71
	v_mul_f32_e32 v77, v75, v71
	v_cvt_pk_bf16_f32 v42, v70, v71
	v_fma_f32 v40, v68, v70, -v76
	v_fma_f32 v41, v69, v70, v77
	ds_write_b16 v103, v42 offset:1360
	v_add_f32_e32 v70, v40, v154
	v_add_f32_e32 v71, v41, v138
	ds_write_b16_d16_hi v103, v42 offset:1488
	v_mul_f32_e32 v76, v74, v71
	v_mul_f32_e32 v77, v75, v71
	v_cvt_pk_bf16_f32 v42, v70, v71
	v_fma_f32 v40, v68, v70, -v76
	v_fma_f32 v41, v69, v70, v77
	ds_write_b16 v103, v42 offset:1632
	v_add_f32_e32 v70, v40, v155
; __device__ __forceinline__ bf f2bf(float f) { return (bf)(pk2(f, 0.f) & 0xFFFFu); }
; __device__ __forceinline__ void s5_pass2(const Params& p, int layer, int task, char* sm) {
;     ...
;       for (int l = 0; l < 32; l++) {
;         S5_STEP(sU + l * 16)
;         sS[l * 136 + lane] = f2bf(sr); sS[l * 136 + 64 + lane] = f2bf(si);
;       }
	v_add_f32_e32 v71, v41, v139
	ds_write_b16_d16_hi v103, v42 offset:1760
	v_mul_f32_e32 v76, v74, v71
	v_mul_f32_e32 v77, v75, v71
	v_cvt_pk_bf16_f32 v42, v70, v71
	v_fma_f32 v40, v68, v70, -v76
	v_fma_f32 v41, v69, v70, v77
	ds_write_b16 v103, v42 offset:1904
	v_add_f32_e32 v70, v40, v108
	v_add_f32_e32 v71, v41, v124
	ds_write_b16_d16_hi v103, v42 offset:2032
	v_mul_f32_e32 v76, v74, v71
	v_mul_f32_e32 v77, v75, v71
	v_cvt_pk_bf16_f32 v42, v70, v71
	v_fma_f32 v40, v68, v70, -v76
	v_fma_f32 v41, v69, v70, v77
	ds_write_b16 v103, v42 offset:2176
	v_add_f32_e32 v70, v40, v109
	v_add_f32_e32 v71, v41, v125
	ds_write_b16_d16_hi v103, v42 offset:2304
	v_mul_f32_e32 v76, v74, v71
	v_mul_f32_e32 v77, v75, v71
	v_cvt_pk_bf16_f32 v42, v70, v71
	v_fma_f32 v40, v68, v70, -v76
	v_fma_f32 v41, v69, v70, v77
	ds_write_b16 v103, v42 offset:2448
	v_add_f32_e32 v70, v40, v110
	v_add_f32_e32 v71, v41, v126
	ds_write_b16_d16_hi v103, v42 offset:2576
	v_mul_f32_e32 v76, v74, v71
	v_mul_f32_e32 v77, v75, v71
	v_cvt_pk_bf16_f32 v42, v70, v71
	v_fma_f32 v40, v68, v70, -v76
	v_fma_f32 v41, v69, v70, v77
	ds_write_b16 v103, v42 offset:2720
	v_add_f32_e32 v70, v40, v111
	v_add_f32_e32 v71, v41, v127
	ds_write_b16_d16_hi v103, v42 offset:2848
	v_mul_f32_e32 v76, v74, v71
	v_mul_f32_e32 v77, v75, v71
	v_cvt_pk_bf16_f32 v42, v70, v71
	v_fma_f32 v40, v68, v70, -v76
	v_fma_f32 v41, v69, v70, v77
	ds_write_b16 v103, v42 offset:2992
	v_add_f32_e32 v70, v40, v156
	v_add_f32_e32 v71, v41, v140
	ds_write_b16_d16_hi v103, v42 offset:3120
	v_mul_f32_e32 v76, v74, v71
	v_mul_f32_e32 v77, v75, v71
	v_cvt_pk_bf16_f32 v42, v70, v71
	v_fma_f32 v40, v68, v70, -v76
	v_fma_f32 v41, v69, v70, v77
	ds_write_b16 v103, v42 offset:3264
	v_add_f32_e32 v70, v40, v157
	v_add_f32_e32 v71, v41, v141
	ds_write_b16_d16_hi v103, v42 offset:3392
	v_mul_f32_e32 v76, v74, v71
	v_mul_f32_e32 v77, v75, v71
	v_cvt_pk_bf16_f32 v42, v70, v71
	v_fma_f32 v40, v68, v70, -v76
	v_fma_f32 v41, v69, v70, v77
	ds_write_b16 v103, v42 offset:3536
	v_add_f32_e32 v70, v40, v158
	v_add_f32_e32 v71, v41, v142
	ds_write_b16_d16_hi v103, v42 offset:3664
	v_mul_f32_e32 v76, v74, v71
	v_mul_f32_e32 v77, v75, v71
	v_cvt_pk_bf16_f32 v42, v70, v71
	v_fma_f32 v40, v68, v70, -v76
	v_fma_f32 v41, v69, v70, v77
	ds_write_b16 v103, v42 offset:3808
	v_add_f32_e32 v70, v40, v159
	v_add_f32_e32 v71, v41, v143
	ds_write_b16_d16_hi v103, v42 offset:3936
	v_mul_f32_e32 v76, v74, v71
	v_mul_f32_e32 v77, v75, v71
	v_cvt_pk_bf16_f32 v42, v70, v71
	v_fma_f32 v40, v68, v70, -v76
	v_fma_f32 v41, v69, v70, v77
	ds_write_b16 v103, v42 offset:4080
	v_add_f32_e32 v70, v40, v112
	v_add_f32_e32 v71, v41, v128
	ds_write_b16_d16_hi v103, v42 offset:4208
	v_mul_f32_e32 v76, v74, v71
	v_mul_f32_e32 v77, v75, v71
	v_cvt_pk_bf16_f32 v42, v70, v71
	v_fma_f32 v40, v68, v70, -v76
	v_fma_f32 v41, v69, v70, v77
	ds_write_b16 v103, v42 offset:4352
	v_add_f32_e32 v70, v40, v113
	v_add_f32_e32 v71, v41, v129
	ds_write_b16_d16_hi v103, v42 offset:4480
	v_mul_f32_e32 v76, v74, v71
	v_mul_f32_e32 v77, v75, v71
	v_cvt_pk_bf16_f32 v42, v70, v71
	v_fma_f32 v40, v68, v70, -v76
	v_fma_f32 v41, v69, v70, v77
	ds_write_b16 v103, v42 offset:4624
	v_add_f32_e32 v70, v40, v114
	v_add_f32_e32 v71, v41, v130
	ds_write_b16_d16_hi v103, v42 offset:4752
	v_mul_f32_e32 v76, v74, v71
	v_mul_f32_e32 v77, v75, v71
	v_cvt_pk_bf16_f32 v42, v70, v71
	v_fma_f32 v40, v68, v70, -v76
	v_fma_f32 v41, v69, v70, v77
	ds_write_b16 v103, v42 offset:4896
	v_add_f32_e32 v70, v40, v115
	v_add_f32_e32 v71, v41, v131
	ds_write_b16_d16_hi v103, v42 offset:5024
	v_mul_f32_e32 v76, v74, v71
	v_mul_f32_e32 v77, v75, v71
	v_cvt_pk_bf16_f32 v42, v70, v71
	v_fma_f32 v40, v68, v70, -v76
	v_fma_f32 v41, v69, v70, v77
	ds_write_b16 v103, v42 offset:5168
	v_add_f32_e32 v70, v40, v160
	v_add_f32_e32 v71, v41, v144
	ds_write_b16_d16_hi v103, v42 offset:5296
	v_mul_f32_e32 v76, v74, v71
	v_mul_f32_e32 v77, v75, v71
	v_cvt_pk_bf16_f32 v42, v70, v71
	v_fma_f32 v40, v68, v70, -v76
	v_fma_f32 v41, v69, v70, v77
	ds_write_b16 v103, v42 offset:5440
	v_add_f32_e32 v70, v40, v161
	v_add_f32_e32 v71, v41, v145
	ds_write_b16_d16_hi v103, v42 offset:5568
	v_mul_f32_e32 v76, v74, v71
	v_mul_f32_e32 v77, v75, v71
	v_cvt_pk_bf16_f32 v42, v70, v71
	v_fma_f32 v40, v68, v70, -v76
	v_fma_f32 v41, v69, v70, v77
	ds_write_b16 v103, v42 offset:5712
	v_add_f32_e32 v70, v40, v162
	v_add_f32_e32 v71, v41, v146
	ds_write_b16_d16_hi v103, v42 offset:5840
	v_mul_f32_e32 v76, v74, v71
	v_mul_f32_e32 v77, v75, v71
	v_cvt_pk_bf16_f32 v42, v70, v71
	v_fma_f32 v40, v68, v70, -v76
	v_fma_f32 v41, v69, v70, v77
	ds_write_b16 v103, v42 offset:5984
	v_add_f32_e32 v70, v40, v163
	v_add_f32_e32 v71, v41, v147
	ds_write_b16_d16_hi v103, v42 offset:6112
	v_mul_f32_e32 v76, v74, v71
	v_mul_f32_e32 v77, v75, v71
	v_cvt_pk_bf16_f32 v42, v70, v71
	v_fma_f32 v40, v68, v70, -v76
	v_fma_f32 v41, v69, v70, v77
	ds_write_b16 v103, v42 offset:6256
	v_add_f32_e32 v70, v40, v116
	v_add_f32_e32 v71, v41, v132
	ds_write_b16_d16_hi v103, v42 offset:6384
	v_mul_f32_e32 v76, v74, v71
	v_mul_f32_e32 v77, v75, v71
	v_cvt_pk_bf16_f32 v42, v70, v71
	v_fma_f32 v40, v68, v70, -v76
	v_fma_f32 v41, v69, v70, v77
	ds_write_b16 v103, v42 offset:6528
	v_add_f32_e32 v70, v40, v117
	v_add_f32_e32 v71, v41, v133
	ds_write_b16_d16_hi v103, v42 offset:6656
	v_mul_f32_e32 v76, v74, v71
	v_mul_f32_e32 v77, v75, v71
	v_cvt_pk_bf16_f32 v42, v70, v71
	v_fma_f32 v40, v68, v70, -v76
	v_fma_f32 v41, v69, v70, v77
	ds_write_b16 v103, v42 offset:6800
	v_add_f32_e32 v70, v40, v118
	v_add_f32_e32 v71, v41, v134
	ds_write_b16_d16_hi v103, v42 offset:6928
	v_mul_f32_e32 v76, v74, v71
; __device__ __forceinline__ float ozero() { float z = 0.f; asm volatile("" : "+v"(z)); return z; }
; __device__ __forceinline__ bf f2bf(float f) { return (bf)(pk2(f, 0.f) & 0xFFFFu); }
; __device__ __forceinline__ f32x4 mfma16(bf16x8 a, bf16x8 b, f32x4 c) { return __builtin_amdgcn_mfma_f32_16x16x32_bf16(a, b, c, 0, 0, 0); }
; __device__ __forceinline__ void s5_pass2(const Params& p, int layer, int task, char* sm) {
;     ...
; #pragma unroll
;       for (int mb = 0; mb < 2; mb++) {
;         const float z_ = ozero(); f32x4 acc = {z_, z_, z_, z_};
; #pragma unroll
;         for (int ks = 0; ks < 4; ks++) {
;           bf16x8 af = *(const bf16x8*)(sS + (16 * mb + (lane & 15)) * 136 + ks * 32 + 8 * (lane >> 4));
;           acc = mfma16(af, cf[ks], acc);
;         }
; #pragma unroll
;         for (int r = 0; r < 4; r++) {
;           const int l = 16 * mb + 4 * (lane >> 4) + r;
;           float y = acc[r] + dsk * sU[l * 16 + (lane & 15)];
;           p.YG[(tok0 + sub * 32 + l) * 512 + g * 16 + (lane & 15)] = f2bf(geluf_(y));
	v_mul_f32_e32 v77, v75, v71
	v_cvt_pk_bf16_f32 v42, v70, v71
	v_fma_f32 v40, v68, v70, -v76
	v_fma_f32 v41, v69, v70, v77
	ds_write_b16 v103, v42 offset:7072
	v_add_f32_e32 v70, v40, v119
	v_add_f32_e32 v71, v41, v135
	ds_write_b16_d16_hi v103, v42 offset:7200
	v_mul_f32_e32 v76, v74, v71
	v_mul_f32_e32 v77, v75, v71
	v_cvt_pk_bf16_f32 v42, v70, v71
	v_fma_f32 v40, v68, v70, -v76
	v_fma_f32 v41, v69, v70, v77
	ds_write_b16 v103, v42 offset:7344
	v_add_f32_e32 v70, v40, v164
	v_add_f32_e32 v71, v41, v148
	ds_write_b16_d16_hi v103, v42 offset:7472
	v_mul_f32_e32 v76, v74, v71
	v_mul_f32_e32 v77, v75, v71
	v_cvt_pk_bf16_f32 v42, v70, v71
	v_fma_f32 v40, v68, v70, -v76
	v_fma_f32 v41, v69, v70, v77
	ds_write_b16 v103, v42 offset:7616
	v_add_f32_e32 v70, v40, v165
	v_add_f32_e32 v71, v41, v149
	ds_write_b16_d16_hi v103, v42 offset:7744
	v_mul_f32_e32 v76, v74, v71
	v_mul_f32_e32 v77, v75, v71
	v_cvt_pk_bf16_f32 v42, v70, v71
	v_fma_f32 v40, v68, v70, -v76
	v_fma_f32 v41, v69, v70, v77
	ds_write_b16 v103, v42 offset:7888
	v_add_f32_e32 v70, v40, v166
	v_add_f32_e32 v71, v41, v150
	ds_write_b16_d16_hi v103, v42 offset:8016
	v_mul_f32_e32 v76, v74, v71
	v_mul_f32_e32 v77, v75, v71
	v_cvt_pk_bf16_f32 v42, v70, v71
	v_fma_f32 v40, v68, v70, -v76
	v_fma_f32 v41, v69, v70, v77
	ds_write_b16 v103, v42 offset:8160
	v_add_f32_e32 v70, v40, v167
	v_add_f32_e32 v71, v41, v151
	ds_write_b16_d16_hi v103, v42 offset:8288
	v_cvt_pk_bf16_f32 v42, v70, v71
	ds_write_b16 v103, v42 offset:8432
	ds_write_b16_d16_hi v103, v42 offset:8560
	s_waitcnt lgkmcnt(0)
	v_mov_b32_e32 v145, 0
	v_mov_b32_e32 v40, v145
	ds_read_b128 v[104:107], v100 offset:2048
	ds_read_b32 v76, v83
	v_mov_b32_e32 v41, v40
	v_mov_b32_e32 v42, v40
	v_mov_b32_e32 v43, v40
	s_lshl_b32 s9, s12, 5
	v_mov_b32_e32 v77, s5
	s_cmp_eq_u32 s8, 4
	s_waitcnt vmcnt(4) lgkmcnt(1)
	v_mfma_f32_16x16x32_bf16 v[40:43], v[104:107], v[24:27], v[40:43]
	ds_read_b128 v[104:107], v100 offset:2112
	s_waitcnt vmcnt(3) lgkmcnt(0)
	v_mfma_f32_16x16x32_bf16 v[40:43], v[104:107], v[28:31], v[40:43]
	ds_read_b128 v[104:107], v100 offset:2176
	s_waitcnt vmcnt(2) lgkmcnt(0)
	v_mfma_f32_16x16x32_bf16 v[40:43], v[104:107], v[32:35], v[40:43]
	ds_read_b128 v[104:107], v100 offset:2240
	s_waitcnt vmcnt(1) lgkmcnt(0)
	v_mfma_f32_16x16x32_bf16 v[40:43], v[104:107], v[36:39], v[40:43]
	s_waitcnt vmcnt(0)
	s_nop 6
	v_fma_f32 v40, v102, v76, v40
	v_mul_f32_e32 v76, 0x3d372713, v40
	v_mul_f32_e32 v76, v40, v76
	v_fma_f32 v76, v40, v76, v40
	v_mul_f32_e32 v76, 0x3f4c422a, v76
	v_add_f32_e32 v76, v76, v76
	v_mul_f32_e32 v76, 0x3fb8aa3b, v76
	v_exp_f32_e32 v76, v76
	v_mul_f32_e32 v40, 0.5, v40
	v_add_f32_e32 v76, 1.0, v76
	v_rcp_f32_e32 v76, v76
	s_nop 0
	v_fma_f32 v76, v76, -2.0, 1.0
	v_add_f32_e32 v76, 1.0, v76
	v_mul_f32_e32 v40, v40, v76
	v_or_b32_e32 v76, s9, v82
	v_or_b32_e32 v76, s4, v76
	v_lshlrev_b64 v[104:105], 10, v[76:77]
	v_cvt_pk_bf16_f32 v40, v40, s0
	v_lshl_add_u64 v[104:105], v[72:73], 0, v[104:105]
	global_store_short v[104:105], v40, off
	ds_read_b32 v40, v85
	s_waitcnt lgkmcnt(0)
	v_fma_f32 v40, v102, v40, v41
	v_mul_f32_e32 v41, 0x3d372713, v40
	v_mul_f32_e32 v41, v40, v41
	v_fma_f32 v41, v40, v41, v40
	v_mul_f32_e32 v41, 0x3f4c422a, v41
	v_add_f32_e32 v41, v41, v41
	v_mul_f32_e32 v41, 0x3fb8aa3b, v41
	v_exp_f32_e32 v41, v41
	v_mul_f32_e32 v40, 0.5, v40
	v_add_f32_e32 v41, 1.0, v41
	v_rcp_f32_e32 v41, v41
	s_nop 0
	v_fma_f32 v41, v41, -2.0, 1.0
	v_add_f32_e32 v41, 1.0, v41
	v_mul_f32_e32 v40, v40, v41
	v_cvt_pk_bf16_f32 v103, v40, s0
	v_or_b32_e32 v40, s9, v84
	v_or_b32_e32 v76, s4, v40
	v_lshlrev_b64 v[40:41], 10, v[76:77]
	v_lshl_add_u64 v[40:41], v[72:73], 0, v[40:41]
	global_store_short v[40:41], v103, off
	ds_read_b32 v40, v87
	s_waitcnt lgkmcnt(0)
	v_fma_f32 v40, v102, v40, v42
	v_mul_f32_e32 v41, 0x3d372713, v40
	v_mul_f32_e32 v41, v40, v41
	v_fma_f32 v41, v40, v41, v40
	v_mul_f32_e32 v41, 0x3f4c422a, v41
	v_add_f32_e32 v41, v41, v41
	v_mul_f32_e32 v41, 0x3fb8aa3b, v41
	v_exp_f32_e32 v41, v41
	v_mul_f32_e32 v40, 0.5, v40
	v_add_f32_e32 v41, 1.0, v41
	v_rcp_f32_e32 v41, v41
	s_nop 0
	v_fma_f32 v41, v41, -2.0, 1.0
	v_add_f32_e32 v41, 1.0, v41
	v_mul_f32_e32 v40, v40, v41
	v_cvt_pk_bf16_f32 v42, v40, s0
	v_or_b32_e32 v40, s9, v86
	v_or_b32_e32 v76, s4, v40
	v_lshlrev_b64 v[40:41], 10, v[76:77]
	v_lshl_add_u64 v[40:41], v[72:73], 0, v[40:41]
	global_store_short v[40:41], v42, off
	ds_read_b32 v40, v89
	s_waitcnt lgkmcnt(0)
; __device__ __forceinline__ float ozero() { float z = 0.f; asm volatile("" : "+v"(z)); return z; }
; __device__ __forceinline__ bf f2bf(float f) { return (bf)(pk2(f, 0.f) & 0xFFFFu); }
; __device__ __forceinline__ f32x4 mfma16(bf16x8 a, bf16x8 b, f32x4 c) { return __builtin_amdgcn_mfma_f32_16x16x32_bf16(a, b, c, 0, 0, 0); }
; __device__ __forceinline__ void s5_pass2(const Params& p, int layer, int task, char* sm) {
;     ...
; #pragma unroll
;       for (int mb = 0; mb < 2; mb++) {
;         const float z_ = ozero(); f32x4 acc = {z_, z_, z_, z_};
; #pragma unroll
;         for (int ks = 0; ks < 4; ks++) {
;           bf16x8 af = *(const bf16x8*)(sS + (16 * mb + (lane & 15)) * 136 + ks * 32 + 8 * (lane >> 4));
;           acc = mfma16(af, cf[ks], acc);
;         }
; #pragma unroll
;         for (int r = 0; r < 4; r++) {
;           const int l = 16 * mb + 4 * (lane >> 4) + r;
;           float y = acc[r] + dsk * sU[l * 16 + (lane & 15)];
;           p.YG[(tok0 + sub * 32 + l) * 512 + g * 16 + (lane & 15)] = f2bf(geluf_(y));
;         }
;       }
	v_fmac_f32_e32 v43, v102, v40
	v_mul_f32_e32 v40, 0x3d372713, v43
	v_mul_f32_e32 v40, v43, v40
	v_fma_f32 v40, v43, v40, v43
	v_mul_f32_e32 v40, 0x3f4c422a, v40
	v_add_f32_e32 v40, v40, v40
	v_mul_f32_e32 v40, 0x3fb8aa3b, v40
	v_exp_f32_e32 v40, v40
	v_mul_f32_e32 v41, 0.5, v43
	v_add_f32_e32 v40, 1.0, v40
	v_rcp_f32_e32 v40, v40
	s_nop 0
	v_fma_f32 v40, v40, -2.0, 1.0
	v_add_f32_e32 v40, 1.0, v40
	v_mul_f32_e32 v40, v41, v40
	v_cvt_pk_bf16_f32 v42, v40, s0
	v_or_b32_e32 v40, s9, v88
	v_or_b32_e32 v76, s4, v40
	v_lshlrev_b64 v[40:41], 10, v[76:77]
	v_lshl_add_u64 v[40:41], v[72:73], 0, v[40:41]
	global_store_short v[40:41], v42, off
	v_mov_b32_e32 v40, v145
	ds_read_b128 v[104:107], v100 offset:6400
	ds_read_b32 v76, v91
	v_mov_b32_e32 v41, v40
	v_mov_b32_e32 v42, v40
	v_mov_b32_e32 v43, v40
	s_waitcnt lgkmcnt(1)
	s_nop 0
	v_mfma_f32_16x16x32_bf16 v[40:43], v[104:107], v[24:27], v[40:43]
	ds_read_b128 v[104:107], v100 offset:6464
	s_waitcnt lgkmcnt(0)
	v_mfma_f32_16x16x32_bf16 v[40:43], v[104:107], v[28:31], v[40:43]
	ds_read_b128 v[104:107], v100 offset:6528
	s_waitcnt lgkmcnt(0)
	v_mfma_f32_16x16x32_bf16 v[40:43], v[104:107], v[32:35], v[40:43]
	ds_read_b128 v[104:107], v100 offset:6592
	s_waitcnt lgkmcnt(0)
	v_mfma_f32_16x16x32_bf16 v[40:43], v[104:107], v[36:39], v[40:43]
	s_nop 7
	v_fma_f32 v40, v102, v76, v40
	v_mul_f32_e32 v76, 0x3d372713, v40
	v_mul_f32_e32 v76, v40, v76
	v_fma_f32 v76, v40, v76, v40
	v_mul_f32_e32 v76, 0x3f4c422a, v76
	v_add_f32_e32 v76, v76, v76
	v_mul_f32_e32 v76, 0x3fb8aa3b, v76
	v_exp_f32_e32 v76, v76
	v_mul_f32_e32 v40, 0.5, v40
	v_add_f32_e32 v76, 1.0, v76
	v_rcp_f32_e32 v76, v76
	s_nop 0
	v_fma_f32 v76, v76, -2.0, 1.0
	v_add_f32_e32 v76, 1.0, v76
	v_mul_f32_e32 v40, v40, v76
	v_or_b32_e32 v76, s9, v90
	v_or_b32_e32 v76, s4, v76
	v_lshlrev_b64 v[104:105], 10, v[76:77]
	v_cvt_pk_bf16_f32 v40, v40, s0
	v_lshl_add_u64 v[104:105], v[72:73], 0, v[104:105]
	global_store_short v[104:105], v40, off
	ds_read_b32 v40, v93
	s_waitcnt lgkmcnt(0)
	v_fma_f32 v40, v102, v40, v41
	v_mul_f32_e32 v41, 0x3d372713, v40
	v_mul_f32_e32 v41, v40, v41
	v_fma_f32 v41, v40, v41, v40
	v_mul_f32_e32 v41, 0x3f4c422a, v41
	v_add_f32_e32 v41, v41, v41
	v_mul_f32_e32 v41, 0x3fb8aa3b, v41
	v_exp_f32_e32 v41, v41
	v_mul_f32_e32 v40, 0.5, v40
	v_add_f32_e32 v41, 1.0, v41
	v_rcp_f32_e32 v41, v41
	s_nop 0
	v_fma_f32 v41, v41, -2.0, 1.0
	v_add_f32_e32 v41, 1.0, v41
	v_mul_f32_e32 v40, v40, v41
	v_cvt_pk_bf16_f32 v103, v40, s0
	v_or_b32_e32 v40, s9, v92
	v_or_b32_e32 v76, s4, v40
	v_lshlrev_b64 v[40:41], 10, v[76:77]
	v_lshl_add_u64 v[40:41], v[72:73], 0, v[40:41]
	global_store_short v[40:41], v103, off
	ds_read_b32 v40, v95
	s_waitcnt lgkmcnt(0)
	v_fma_f32 v40, v102, v40, v42
	v_mul_f32_e32 v41, 0x3d372713, v40
	v_mul_f32_e32 v41, v40, v41
	v_fma_f32 v41, v40, v41, v40
	v_mul_f32_e32 v41, 0x3f4c422a, v41
	v_add_f32_e32 v41, v41, v41
	v_mul_f32_e32 v41, 0x3fb8aa3b, v41
	v_exp_f32_e32 v41, v41
	v_mul_f32_e32 v40, 0.5, v40
	v_add_f32_e32 v41, 1.0, v41
	v_rcp_f32_e32 v41, v41
	s_nop 0
	v_fma_f32 v41, v41, -2.0, 1.0
	v_add_f32_e32 v41, 1.0, v41
	v_mul_f32_e32 v40, v40, v41
	v_cvt_pk_bf16_f32 v42, v40, s0
	v_or_b32_e32 v40, s9, v94
	v_or_b32_e32 v76, s4, v40
	v_lshlrev_b64 v[40:41], 10, v[76:77]
	v_lshl_add_u64 v[40:41], v[72:73], 0, v[40:41]
	global_store_short v[40:41], v42, off
	ds_read_b32 v40, v97
	s_waitcnt lgkmcnt(0)
	v_fmac_f32_e32 v43, v102, v40
	v_mul_f32_e32 v40, 0x3d372713, v43
	v_mul_f32_e32 v40, v43, v40
	v_fma_f32 v40, v43, v40, v43
	v_mul_f32_e32 v40, 0x3f4c422a, v40
	v_add_f32_e32 v40, v40, v40
	v_mul_f32_e32 v40, 0x3fb8aa3b, v40
	v_exp_f32_e32 v40, v40
	v_mul_f32_e32 v41, 0.5, v43
	v_add_f32_e32 v40, 1.0, v40
	v_rcp_f32_e32 v40, v40
	s_nop 0
	v_fma_f32 v40, v40, -2.0, 1.0
	v_add_f32_e32 v40, 1.0, v40
	v_mul_f32_e32 v40, v41, v40
	v_cvt_pk_bf16_f32 v42, v40, s0
	v_or_b32_e32 v40, s9, v96
	v_or_b32_e32 v76, s4, v40
	v_lshlrev_b64 v[40:41], 10, v[76:77]
	v_lshl_add_u64 v[40:41], v[72:73], 0, v[40:41]
	global_store_short v[40:41], v42, off
	s_cbranch_scc1 .LBB0_2053
	s_mov_b32 s12, s8
	s_branch .LBB0_2055
